# K-loops: setprio 1 moved before barrier, redundant lgkmcnt wait after barrier removed, mid-phase prio flips dropped, setprio 0 after barrier
# speedup vs baseline: 1.0037x; 1.0037x over previous
; #define PG8_STAGE(bufoff, gbase, voff) do { _Pragma("unroll") for (int _i = 0; _i < 2; ++_i) \
;         __builtin_amdgcn_global_load_lds((const unsigned*)((const char*)(gbase) + (voff)[_i]), (PG8_LAS unsigned*)(lds + (bufoff) + ldsw + _i * 8192), 16, 0, 0); } while (0)
; #define PG8_LDA(dst, b, h) do { _Pragma("unroll") for (int m = 0; m < 4; ++m) _Pragma("unroll") for (int k = 0; k < 2; ++k) dst[m][k] = *(const PG8_LAS bf16x8*)(lds + PG8_SA(b, h) + aoff + m * 2048 + k * 1024); } while (0)
; #define PG8_LDB(dst, b, h) do { _Pragma("unroll") for (int n = 0; n < 2; ++n) _Pragma("unroll") for (int k = 0; k < 2; ++k) dst[n][k] = *(const PG8_LAS bf16x8*)(lds + PG8_SB(b, h) + boff + n * 2048 + k * 1024); } while (0)
; #define PG8_MMA(ai, bj, At, Bt) do { __builtin_amdgcn_s_setprio(1); _Pragma("unroll") for (int m = 0; m < 4; ++m) _Pragma("unroll") for (int n = 0; n < 2; ++n) _Pragma("unroll") for (int k = 0; k < 2; ++k) \
;         acc[ai][bj][m][n] = __builtin_amdgcn_mfma_f32_16x16x32_bf16(Bt[n][k], At[m][k], acc[ai][bj][m][n], 0, 0, 0); __builtin_amdgcn_s_setprio(0); } while (0)
; #define PG8_WAIT_V(n) asm volatile("s_waitcnt vmcnt(" #n ")" ::: "memory")
; #define PG8_WAIT_L(n) asm volatile("s_waitcnt lgkmcnt(" #n ")" ::: "memory")
; #define PG8_BAR __builtin_amdgcn_s_barrier()
; #define PG8_SCHED __builtin_amdgcn_sched_barrier(0)
; template <class Epi, class Sched, bool ALIGN_EPI = false, bool SP2 = false>
; __device__ __forceinline__ void gemm_phase(PG8_LAS unsigned char* lds, const Gemm g, const Sched& S, const Epi& E) {
;     ...
;             PG8_LDB(B0, 0, 0); PG8_LDB(B1, 0, 1); PG8_SCHED; PG8_LDA(At, 0, 0); PG8_STAGE(PG8_SA(1, 1), a1 + hstep, voffA);
;             PG8_WAIT_V(8); PG8_WAIT_L(0); PG8_BAR; PG8_MMA(0, 0, At, B0); PG8_MMA(0, 1, At, B1); PG8_BAR; PG8_SCHED;
;             PG8_LDA(At, 0, 1); PG8_STAGE(PG8_SB(0, 0), b2, voffB); PG8_STAGE(PG8_SB(0, 1), b2 + hstep, voffB); PG8_STAGE(PG8_SA(0, 0), a2, voffA);
;             PG8_WAIT_V(8); PG8_WAIT_L(0); PG8_BAR; PG8_MMA(1, 0, At, B0); PG8_MMA(1, 1, At, B1); PG8_BAR; PG8_SCHED;
.LBB0_115:
	s_add_u32 s6, s4, 0xfff80080
	s_addc_u32 s7, s5, -1
	s_add_i32 s53, 0, 0x10000
	s_cmp_eq_u32 s52, 28
	s_cselect_b32 s9, s21, s7
	s_cselect_b32 s8, s26, s6
	s_cselect_b32 s7, s19, s29
	s_cselect_b32 s6, s27, s28
	s_add_i32 s56, 0, 0x14000
	v_add_u32_e32 v142, s53, v162
	v_add_u32_e32 v156, s56, v162
	ds_read_b128 v[130:133], v142
	ds_read_b128 v[134:137], v142 offset:1024
	ds_read_b128 v[138:141], v142 offset:2048
	ds_read_b128 v[142:145], v142 offset:3072
	ds_read_b128 v[178:181], v156
	ds_read_b128 v[182:185], v156 offset:1024
	ds_read_b128 v[200:203], v156 offset:2048
	ds_read_b128 v[204:207], v156 offset:3072
	v_lshl_add_u64 v[156:157], s[4:5], 0, v[152:153]
	s_add_i32 m0, s34, 0xc000
	ds_read_b128 v[208:211], v176
	ds_read_b128 v[212:215], v176 offset:1024
	ds_read_b128 v[216:219], v176 offset:2048
	ds_read_b128 v[220:223], v176 offset:3072
	ds_read_b128 v[224:227], v176 offset:4096
	ds_read_b128 v[228:231], v176 offset:5120
	ds_read_b128 v[232:235], v176 offset:6144
	ds_read_b128 v[236:239], v176 offset:7168
	global_load_lds_dwordx4 v[156:157], off
	v_lshl_add_u64 v[156:157], s[4:5], 0, v[154:155]
	s_add_i32 m0, s34, 0xe000
	s_nop 0
	global_load_lds_dwordx4 v[156:157], off
	s_waitcnt vmcnt(8)
	s_waitcnt lgkmcnt(0)
	s_setprio 1
	s_barrier
	v_mfma_f32_16x16x32_bf16 v[126:129], v[130:133], v[208:211], v[126:129]
	v_mfma_f32_16x16x32_bf16 v[122:125], v[138:141], v[208:211], v[122:125]
	v_mfma_f32_16x16x32_bf16 v[118:121], v[130:133], v[216:219], v[118:121]
	v_mfma_f32_16x16x32_bf16 v[110:113], v[138:141], v[216:219], v[110:113]
	v_mfma_f32_16x16x32_bf16 v[102:105], v[130:133], v[224:227], v[102:105]
	v_mfma_f32_16x16x32_bf16 v[94:97], v[138:141], v[224:227], v[94:97]
	v_mfma_f32_16x16x32_bf16 v[86:89], v[130:133], v[232:235], v[86:89]
	v_mfma_f32_16x16x32_bf16 v[78:81], v[138:141], v[232:235], v[78:81]
	v_mfma_f32_16x16x32_bf16 v[126:129], v[134:137], v[212:215], v[126:129]
	v_mfma_f32_16x16x32_bf16 v[122:125], v[142:145], v[212:215], v[122:125]
	v_mfma_f32_16x16x32_bf16 v[118:121], v[134:137], v[220:223], v[118:121]
	v_mfma_f32_16x16x32_bf16 v[110:113], v[142:145], v[220:223], v[110:113]
	v_mfma_f32_16x16x32_bf16 v[102:105], v[134:137], v[228:231], v[102:105]
	v_mfma_f32_16x16x32_bf16 v[94:97], v[142:145], v[228:231], v[94:97]
	v_mfma_f32_16x16x32_bf16 v[86:89], v[134:137], v[236:239], v[86:89]
	v_mfma_f32_16x16x32_bf16 v[78:81], v[142:145], v[236:239], v[78:81]
	v_mfma_f32_16x16x32_bf16 v[114:117], v[178:181], v[208:211], v[114:117]
	v_mfma_f32_16x16x32_bf16 v[106:109], v[200:203], v[208:211], v[106:109]
	v_mfma_f32_16x16x32_bf16 v[98:101], v[178:181], v[216:219], v[98:101]
	v_mfma_f32_16x16x32_bf16 v[90:93], v[200:203], v[216:219], v[90:93]
	v_mfma_f32_16x16x32_bf16 v[82:85], v[178:181], v[224:227], v[82:85]
	v_mfma_f32_16x16x32_bf16 v[74:77], v[200:203], v[224:227], v[74:77]
	v_mfma_f32_16x16x32_bf16 v[70:73], v[178:181], v[232:235], v[70:73]
	v_mfma_f32_16x16x32_bf16 v[66:69], v[200:203], v[232:235], v[66:69]
	v_mfma_f32_16x16x32_bf16 v[114:117], v[182:185], v[212:215], v[114:117]
	v_mfma_f32_16x16x32_bf16 v[106:109], v[204:207], v[212:215], v[106:109]
	v_mfma_f32_16x16x32_bf16 v[98:101], v[182:185], v[220:223], v[98:101]
	v_mfma_f32_16x16x32_bf16 v[90:93], v[204:207], v[220:223], v[90:93]
	v_mfma_f32_16x16x32_bf16 v[82:85], v[182:185], v[228:231], v[82:85]
	v_mfma_f32_16x16x32_bf16 v[74:77], v[204:207], v[228:231], v[74:77]
	v_mfma_f32_16x16x32_bf16 v[70:73], v[182:185], v[236:239], v[70:73]
	v_mfma_f32_16x16x32_bf16 v[66:69], v[204:207], v[236:239], v[66:69]
	s_barrier
	s_setprio 0
	s_add_i32 s53, s53, s33
	v_lshl_add_u64 v[156:157], s[6:7], 0, v[0:1]
	s_mov_b32 m0, s53
	ds_read_b128 v[208:211], v176 offset:16384
	ds_read_b128 v[212:215], v176 offset:17408
	ds_read_b128 v[216:219], v176 offset:18432
	ds_read_b128 v[220:223], v176 offset:19456
	ds_read_b128 v[224:227], v176 offset:20480
	ds_read_b128 v[228:231], v176 offset:21504
	ds_read_b128 v[232:235], v176 offset:22528
	ds_read_b128 v[236:239], v176 offset:23552
	global_load_lds_dwordx4 v[156:157], off
	s_add_i32 m0, s53, 0x2000
	s_add_u32 s54, s6, 0x80000
	v_lshl_add_u64 v[164:165], s[6:7], 0, v[146:147]
	s_addc_u32 s55, s7, 0
	s_add_i32 s53, s56, s33
	global_load_lds_dwordx4 v[164:165], off
	v_lshl_add_u64 v[166:167], s[54:55], 0, v[0:1]
	s_mov_b32 m0, s53
	v_lshl_add_u64 v[172:173], s[8:9], 0, v[148:149]
	global_load_lds_dwordx4 v[166:167], off
	v_lshl_add_u64 v[166:167], s[54:55], 0, v[146:147]
	s_add_i32 m0, s53, 0x2000
	s_nop 0
	global_load_lds_dwordx4 v[166:167], off
	v_lshl_add_u64 v[166:167], s[8:9], 0, v[150:151]
	s_mov_b32 m0, s34
	s_nop 0
	global_load_lds_dwordx4 v[166:167], off
	s_mov_b32 m0, s35
	s_nop 0
	global_load_lds_dwordx4 v[172:173], off
	s_waitcnt vmcnt(8)
	s_waitcnt lgkmcnt(0)
	s_setprio 1
	s_barrier
; #define PG8_STAGE(bufoff, gbase, voff) do { _Pragma("unroll") for (int _i = 0; _i < 2; ++_i) \
;         __builtin_amdgcn_global_load_lds((const unsigned*)((const char*)(gbase) + (voff)[_i]), (PG8_LAS unsigned*)(lds + (bufoff) + ldsw + _i * 8192), 16, 0, 0); } while (0)
; #define PG8_LDA(dst, b, h) do { _Pragma("unroll") for (int m = 0; m < 4; ++m) _Pragma("unroll") for (int k = 0; k < 2; ++k) dst[m][k] = *(const PG8_LAS bf16x8*)(lds + PG8_SA(b, h) + aoff + m * 2048 + k * 1024); } while (0)
; #define PG8_LDB(dst, b, h) do { _Pragma("unroll") for (int n = 0; n < 2; ++n) _Pragma("unroll") for (int k = 0; k < 2; ++k) dst[n][k] = *(const PG8_LAS bf16x8*)(lds + PG8_SB(b, h) + boff + n * 2048 + k * 1024); } while (0)
; #define PG8_MMA(ai, bj, At, Bt) do { __builtin_amdgcn_s_setprio(1); _Pragma("unroll") for (int m = 0; m < 4; ++m) _Pragma("unroll") for (int n = 0; n < 2; ++n) _Pragma("unroll") for (int k = 0; k < 2; ++k) \
;         acc[ai][bj][m][n] = __builtin_amdgcn_mfma_f32_16x16x32_bf16(Bt[n][k], At[m][k], acc[ai][bj][m][n], 0, 0, 0); __builtin_amdgcn_s_setprio(0); } while (0)
; #define PG8_WAIT_V(n) asm volatile("s_waitcnt vmcnt(" #n ")" ::: "memory")
; #define PG8_WAIT_L(n) asm volatile("s_waitcnt lgkmcnt(" #n ")" ::: "memory")
; #define PG8_BAR __builtin_amdgcn_s_barrier()
; #define PG8_SCHED __builtin_amdgcn_sched_barrier(0)
; template <class Epi, class Sched, bool ALIGN_EPI = false, bool SP2 = false>
; __device__ __forceinline__ void gemm_phase(PG8_LAS unsigned char* lds, const Gemm g, const Sched& S, const Epi& E) {
;     ...
;             PG8_WAIT_V(8); PG8_WAIT_L(0); PG8_BAR; PG8_MMA(1, 0, At, B0); PG8_MMA(1, 1, At, B1); PG8_BAR; PG8_SCHED;
;             PG8_LDB(B0, 1, 0); PG8_LDB(B1, 1, 1); PG8_SCHED; PG8_LDA(At, 1, 0); PG8_STAGE(PG8_SA(0, 1), a2 + hstep, voffA);
;             PG8_WAIT_V(8); PG8_WAIT_L(0); PG8_BAR; PG8_MMA(0, 0, At, B0); PG8_MMA(0, 1, At, B1); PG8_BAR; PG8_SCHED;
	v_mfma_f32_16x16x32_bf16 v[62:65], v[130:133], v[208:211], v[62:65]
	v_mfma_f32_16x16x32_bf16 v[58:61], v[138:141], v[208:211], v[58:61]
	v_mfma_f32_16x16x32_bf16 v[54:57], v[130:133], v[216:219], v[54:57]
	v_mfma_f32_16x16x32_bf16 v[46:49], v[138:141], v[216:219], v[46:49]
	v_mfma_f32_16x16x32_bf16 v[38:41], v[130:133], v[224:227], v[38:41]
	v_mfma_f32_16x16x32_bf16 v[30:33], v[138:141], v[224:227], v[30:33]
	v_mfma_f32_16x16x32_bf16 v[22:25], v[130:133], v[232:235], v[22:25]
	v_mfma_f32_16x16x32_bf16 v[14:17], v[138:141], v[232:235], v[14:17]
	v_mfma_f32_16x16x32_bf16 v[62:65], v[134:137], v[212:215], v[62:65]
	v_mfma_f32_16x16x32_bf16 v[58:61], v[142:145], v[212:215], v[58:61]
	v_mfma_f32_16x16x32_bf16 v[54:57], v[134:137], v[220:223], v[54:57]
	v_mfma_f32_16x16x32_bf16 v[46:49], v[142:145], v[220:223], v[46:49]
	v_mfma_f32_16x16x32_bf16 v[38:41], v[134:137], v[228:231], v[38:41]
	v_mfma_f32_16x16x32_bf16 v[30:33], v[142:145], v[228:231], v[30:33]
	v_mfma_f32_16x16x32_bf16 v[22:25], v[134:137], v[236:239], v[22:25]
	v_mfma_f32_16x16x32_bf16 v[14:17], v[142:145], v[236:239], v[14:17]
	v_mfma_f32_16x16x32_bf16 v[50:53], v[178:181], v[208:211], v[50:53]
	v_mfma_f32_16x16x32_bf16 v[42:45], v[200:203], v[208:211], v[42:45]
	v_mfma_f32_16x16x32_bf16 v[34:37], v[178:181], v[216:219], v[34:37]
	v_mfma_f32_16x16x32_bf16 v[26:29], v[200:203], v[216:219], v[26:29]
	v_mfma_f32_16x16x32_bf16 v[18:21], v[178:181], v[224:227], v[18:21]
	v_mfma_f32_16x16x32_bf16 v[10:13], v[200:203], v[224:227], v[10:13]
	v_mfma_f32_16x16x32_bf16 v[6:9], v[178:181], v[232:235], v[6:9]
	v_mfma_f32_16x16x32_bf16 v[2:5], v[200:203], v[232:235], v[2:5]
	v_mfma_f32_16x16x32_bf16 v[50:53], v[182:185], v[212:215], v[50:53]
	v_mfma_f32_16x16x32_bf16 v[42:45], v[204:207], v[212:215], v[42:45]
	v_mfma_f32_16x16x32_bf16 v[34:37], v[182:185], v[220:223], v[34:37]
	v_mfma_f32_16x16x32_bf16 v[26:29], v[204:207], v[220:223], v[26:29]
	v_mfma_f32_16x16x32_bf16 v[18:21], v[182:185], v[228:231], v[18:21]
	v_mfma_f32_16x16x32_bf16 v[10:13], v[204:207], v[228:231], v[10:13]
	v_mfma_f32_16x16x32_bf16 v[6:9], v[182:185], v[236:239], v[6:9]
	v_mfma_f32_16x16x32_bf16 v[2:5], v[204:207], v[236:239], v[2:5]
	s_barrier
	s_setprio 0
	s_add_i32 s53, 0, 0x18000
	s_add_i32 s54, 0, 0x1c000
	v_add_u32_e32 v142, s53, v162
	v_add_u32_e32 v158, s54, v162
	ds_read_b128 v[130:133], v142
	ds_read_b128 v[134:137], v142 offset:1024
	ds_read_b128 v[138:141], v142 offset:2048
	ds_read_b128 v[142:145], v142 offset:3072
	ds_read_b128 v[178:181], v158
	ds_read_b128 v[182:185], v158 offset:1024
	ds_read_b128 v[200:203], v158 offset:2048
	ds_read_b128 v[204:207], v158 offset:3072
	s_add_u32 s8, s8, 0x80000
	s_addc_u32 s9, s9, 0
	s_mov_b32 m0, s36
	v_lshl_add_u64 v[174:175], s[8:9], 0, v[150:151]
	ds_read_b128 v[208:211], v176 offset:32768
	ds_read_b128 v[212:215], v176 offset:33792
	ds_read_b128 v[216:219], v176 offset:34816
	ds_read_b128 v[220:223], v176 offset:35840
	ds_read_b128 v[224:227], v176 offset:36864
	ds_read_b128 v[228:231], v176 offset:37888
	ds_read_b128 v[232:235], v176 offset:38912
	ds_read_b128 v[236:239], v176 offset:39936
	global_load_lds_dwordx4 v[174:175], off
	v_lshl_add_u64 v[174:175], s[8:9], 0, v[148:149]
	s_mov_b32 m0, s37
	s_nop 0
	global_load_lds_dwordx4 v[174:175], off
	s_waitcnt vmcnt(8)
	s_waitcnt lgkmcnt(0)
	s_setprio 1
	s_barrier
	v_mfma_f32_16x16x32_bf16 v[126:129], v[130:133], v[208:211], v[126:129]
	v_mfma_f32_16x16x32_bf16 v[122:125], v[138:141], v[208:211], v[122:125]
	v_mfma_f32_16x16x32_bf16 v[118:121], v[130:133], v[216:219], v[118:121]
	v_mfma_f32_16x16x32_bf16 v[110:113], v[138:141], v[216:219], v[110:113]
	v_mfma_f32_16x16x32_bf16 v[102:105], v[130:133], v[224:227], v[102:105]
	v_mfma_f32_16x16x32_bf16 v[94:97], v[138:141], v[224:227], v[94:97]
	v_mfma_f32_16x16x32_bf16 v[86:89], v[130:133], v[232:235], v[86:89]
	v_mfma_f32_16x16x32_bf16 v[78:81], v[138:141], v[232:235], v[78:81]
	v_mfma_f32_16x16x32_bf16 v[126:129], v[134:137], v[212:215], v[126:129]
	v_mfma_f32_16x16x32_bf16 v[122:125], v[142:145], v[212:215], v[122:125]
	v_mfma_f32_16x16x32_bf16 v[118:121], v[134:137], v[220:223], v[118:121]
	v_mfma_f32_16x16x32_bf16 v[110:113], v[142:145], v[220:223], v[110:113]
	v_mfma_f32_16x16x32_bf16 v[102:105], v[134:137], v[228:231], v[102:105]
	v_mfma_f32_16x16x32_bf16 v[94:97], v[142:145], v[228:231], v[94:97]
	v_mfma_f32_16x16x32_bf16 v[86:89], v[134:137], v[236:239], v[86:89]
	v_mfma_f32_16x16x32_bf16 v[78:81], v[142:145], v[236:239], v[78:81]
	v_mfma_f32_16x16x32_bf16 v[114:117], v[178:181], v[208:211], v[114:117]
	v_mfma_f32_16x16x32_bf16 v[106:109], v[200:203], v[208:211], v[106:109]
	v_mfma_f32_16x16x32_bf16 v[98:101], v[178:181], v[216:219], v[98:101]
	v_mfma_f32_16x16x32_bf16 v[90:93], v[200:203], v[216:219], v[90:93]
	v_mfma_f32_16x16x32_bf16 v[82:85], v[178:181], v[224:227], v[82:85]
	v_mfma_f32_16x16x32_bf16 v[74:77], v[200:203], v[224:227], v[74:77]
	v_mfma_f32_16x16x32_bf16 v[70:73], v[178:181], v[232:235], v[70:73]
	v_mfma_f32_16x16x32_bf16 v[66:69], v[200:203], v[232:235], v[66:69]
	v_mfma_f32_16x16x32_bf16 v[114:117], v[182:185], v[212:215], v[114:117]
	v_mfma_f32_16x16x32_bf16 v[106:109], v[204:207], v[212:215], v[106:109]
	v_mfma_f32_16x16x32_bf16 v[98:101], v[182:185], v[220:223], v[98:101]
	v_mfma_f32_16x16x32_bf16 v[90:93], v[204:207], v[220:223], v[90:93]
	v_mfma_f32_16x16x32_bf16 v[82:85], v[182:185], v[228:231], v[82:85]
	v_mfma_f32_16x16x32_bf16 v[74:77], v[204:207], v[228:231], v[74:77]
	v_mfma_f32_16x16x32_bf16 v[70:73], v[182:185], v[236:239], v[70:73]
	v_mfma_f32_16x16x32_bf16 v[66:69], v[204:207], v[236:239], v[66:69]
	s_barrier
; #define PG8_STAGE(bufoff, gbase, voff) do { _Pragma("unroll") for (int _i = 0; _i < 2; ++_i) \
;         __builtin_amdgcn_global_load_lds((const unsigned*)((const char*)(gbase) + (voff)[_i]), (PG8_LAS unsigned*)(lds + (bufoff) + ldsw + _i * 8192), 16, 0, 0); } while (0)
; #define PG8_LDA(dst, b, h) do { _Pragma("unroll") for (int m = 0; m < 4; ++m) _Pragma("unroll") for (int k = 0; k < 2; ++k) dst[m][k] = *(const PG8_LAS bf16x8*)(lds + PG8_SA(b, h) + aoff + m * 2048 + k * 1024); } while (0)
; #define PG8_MMA(ai, bj, At, Bt) do { __builtin_amdgcn_s_setprio(1); _Pragma("unroll") for (int m = 0; m < 4; ++m) _Pragma("unroll") for (int n = 0; n < 2; ++n) _Pragma("unroll") for (int k = 0; k < 2; ++k) \
;         acc[ai][bj][m][n] = __builtin_amdgcn_mfma_f32_16x16x32_bf16(Bt[n][k], At[m][k], acc[ai][bj][m][n], 0, 0, 0); __builtin_amdgcn_s_setprio(0); } while (0)
; #define PG8_WAIT_V(n) asm volatile("s_waitcnt vmcnt(" #n ")" ::: "memory")
; #define PG8_WAIT_L(n) asm volatile("s_waitcnt lgkmcnt(" #n ")" ::: "memory")
; #define PG8_BAR __builtin_amdgcn_s_barrier()
; #define PG8_SCHED __builtin_amdgcn_sched_barrier(0)
; template <class Epi, class Sched, bool ALIGN_EPI = false, bool SP2 = false>
; __device__ __forceinline__ void gemm_phase(PG8_LAS unsigned char* lds, const Gemm g, const Sched& S, const Epi& E) {
;     ...
;             PG8_LDA(At, 1, 1); PG8_STAGE(PG8_SB(1, 0), b3, voffB); PG8_STAGE(PG8_SB(1, 1), b3 + hstep, voffB); PG8_STAGE(PG8_SA(1, 0), a3, voffA);
;             PG8_WAIT_V(8); PG8_WAIT_L(0); PG8_BAR; PG8_MMA(1, 0, At, B0); PG8_MMA(1, 1, At, B1); PG8_BAR; PG8_SCHED;
;     ...
;         if constexpr (ALIGN_EPI) { if (wr == 0) PG8_BAR; }
	s_setprio 0
	s_add_i32 s8, s53, s33
	v_lshl_add_u64 v[156:157], v[156:157], 0, s[44:45]
	s_mov_b32 m0, s8
	ds_read_b128 v[208:211], v176 offset:49152
	ds_read_b128 v[212:215], v176 offset:50176
	ds_read_b128 v[216:219], v176 offset:51200
	ds_read_b128 v[220:223], v176 offset:52224
	ds_read_b128 v[224:227], v176 offset:53248
	ds_read_b128 v[228:231], v176 offset:54272
	ds_read_b128 v[232:235], v176 offset:55296
	ds_read_b128 v[236:239], v176 offset:56320
	global_load_lds_dwordx4 v[156:157], off
	s_add_i32 m0, s8, 0x2000
	s_add_u32 s6, s6, 0x80080
	v_lshl_add_u64 v[156:157], v[164:165], 0, s[44:45]
	s_addc_u32 s7, s7, 0
	s_add_i32 s8, s54, s33
	global_load_lds_dwordx4 v[156:157], off
	v_lshl_add_u64 v[156:157], s[6:7], 0, v[0:1]
	s_mov_b32 m0, s8
	s_nop 0
	global_load_lds_dwordx4 v[156:157], off
	v_lshl_add_u64 v[156:157], s[6:7], 0, v[146:147]
	s_add_i32 m0, s8, 0x2000
	s_nop 0
	global_load_lds_dwordx4 v[156:157], off
	v_lshl_add_u64 v[156:157], v[166:167], 0, s[44:45]
	s_mov_b32 m0, s41
	s_nop 0
	global_load_lds_dwordx4 v[156:157], off
	v_lshl_add_u64 v[156:157], v[172:173], 0, s[44:45]
	s_mov_b32 m0, s42
	s_nop 0
	global_load_lds_dwordx4 v[156:157], off
	s_waitcnt vmcnt(8)
	s_waitcnt lgkmcnt(0)
	s_setprio 1
	s_barrier
	v_mfma_f32_16x16x32_bf16 v[62:65], v[130:133], v[208:211], v[62:65]
	v_mfma_f32_16x16x32_bf16 v[58:61], v[138:141], v[208:211], v[58:61]
	v_mfma_f32_16x16x32_bf16 v[54:57], v[130:133], v[216:219], v[54:57]
	v_mfma_f32_16x16x32_bf16 v[46:49], v[138:141], v[216:219], v[46:49]
	v_mfma_f32_16x16x32_bf16 v[38:41], v[130:133], v[224:227], v[38:41]
	v_mfma_f32_16x16x32_bf16 v[30:33], v[138:141], v[224:227], v[30:33]
	v_mfma_f32_16x16x32_bf16 v[22:25], v[130:133], v[232:235], v[22:25]
	v_mfma_f32_16x16x32_bf16 v[14:17], v[138:141], v[232:235], v[14:17]
	v_mfma_f32_16x16x32_bf16 v[62:65], v[134:137], v[212:215], v[62:65]
	v_mfma_f32_16x16x32_bf16 v[58:61], v[142:145], v[212:215], v[58:61]
	v_mfma_f32_16x16x32_bf16 v[54:57], v[134:137], v[220:223], v[54:57]
	v_mfma_f32_16x16x32_bf16 v[46:49], v[142:145], v[220:223], v[46:49]
	v_mfma_f32_16x16x32_bf16 v[38:41], v[134:137], v[228:231], v[38:41]
	v_mfma_f32_16x16x32_bf16 v[30:33], v[142:145], v[228:231], v[30:33]
	v_mfma_f32_16x16x32_bf16 v[22:25], v[134:137], v[236:239], v[22:25]
	v_mfma_f32_16x16x32_bf16 v[14:17], v[142:145], v[236:239], v[14:17]
	v_mfma_f32_16x16x32_bf16 v[50:53], v[178:181], v[208:211], v[50:53]
	v_mfma_f32_16x16x32_bf16 v[42:45], v[200:203], v[208:211], v[42:45]
	v_mfma_f32_16x16x32_bf16 v[34:37], v[178:181], v[216:219], v[34:37]
	v_mfma_f32_16x16x32_bf16 v[26:29], v[200:203], v[216:219], v[26:29]
	v_mfma_f32_16x16x32_bf16 v[18:21], v[178:181], v[224:227], v[18:21]
	v_mfma_f32_16x16x32_bf16 v[10:13], v[200:203], v[224:227], v[10:13]
	v_mfma_f32_16x16x32_bf16 v[6:9], v[178:181], v[232:235], v[6:9]
	v_mfma_f32_16x16x32_bf16 v[2:5], v[200:203], v[232:235], v[2:5]
	v_mfma_f32_16x16x32_bf16 v[50:53], v[182:185], v[212:215], v[50:53]
	v_mfma_f32_16x16x32_bf16 v[42:45], v[204:207], v[212:215], v[42:45]
	v_mfma_f32_16x16x32_bf16 v[34:37], v[182:185], v[220:223], v[34:37]
	v_mfma_f32_16x16x32_bf16 v[26:29], v[204:207], v[220:223], v[26:29]
	v_mfma_f32_16x16x32_bf16 v[18:21], v[182:185], v[228:231], v[18:21]
	v_mfma_f32_16x16x32_bf16 v[10:13], v[204:207], v[228:231], v[10:13]
	v_mfma_f32_16x16x32_bf16 v[6:9], v[182:185], v[236:239], v[6:9]
	v_mfma_f32_16x16x32_bf16 v[2:5], v[204:207], v[236:239], v[2:5]
	s_barrier
	s_setprio 0
	s_add_i32 s52, s52, 2
	s_add_u32 s4, s4, 0x100
	s_addc_u32 s5, s5, 0
	s_add_u32 s28, s28, 0x100
	s_addc_u32 s29, s29, 0
	s_cmp_gt_u32 s52, 29
	s_cbranch_scc0 .LBB0_115
	s_and_b64 vcc, exec, s[16:17]
	s_cbranch_vccz .LBB0_118
	s_barrier

; #define PG8_STAGE(bufoff, gbase, voff) do { _Pragma("unroll") for (int _i = 0; _i < 2; ++_i) \
;         __builtin_amdgcn_global_load_lds((const unsigned*)((const char*)(gbase) + (voff)[_i]), (PG8_LAS unsigned*)(lds + (bufoff) + ldsw + _i * 8192), 16, 0, 0); } while (0)
; #define PG8_LDA(dst, b, h) do { _Pragma("unroll") for (int m = 0; m < 4; ++m) _Pragma("unroll") for (int k = 0; k < 2; ++k) dst[m][k] = *(const PG8_LAS bf16x8*)(lds + PG8_SA(b, h) + aoff + m * 2048 + k * 1024); } while (0)
; #define PG8_LDB(dst, b, h) do { _Pragma("unroll") for (int n = 0; n < 2; ++n) _Pragma("unroll") for (int k = 0; k < 2; ++k) dst[n][k] = *(const PG8_LAS bf16x8*)(lds + PG8_SB(b, h) + boff + n * 2048 + k * 1024); } while (0)
; #define PG8_MMA(ai, bj, At, Bt) do { __builtin_amdgcn_s_setprio(1); _Pragma("unroll") for (int m = 0; m < 4; ++m) _Pragma("unroll") for (int n = 0; n < 2; ++n) _Pragma("unroll") for (int k = 0; k < 2; ++k) \
;         acc[ai][bj][m][n] = __builtin_amdgcn_mfma_f32_16x16x32_bf16(Bt[n][k], At[m][k], acc[ai][bj][m][n], 0, 0, 0); __builtin_amdgcn_s_setprio(0); } while (0)
; #define PG8_WAIT_V(n) asm volatile("s_waitcnt vmcnt(" #n ")" ::: "memory")
; #define PG8_WAIT_L(n) asm volatile("s_waitcnt lgkmcnt(" #n ")" ::: "memory")
; template <class Epi, class Sched, bool ALIGN_EPI = false, bool SP2 = false>
; __device__ __forceinline__ void gemm_phase(PG8_LAS unsigned char* lds, const Gemm g, const Sched& S, const Epi& E) {
;     ...
;             const bool last = (t == nt - 2);
;             const char* a1 = cA + (size_t)(t + 1) * kstep;
;             const char* a2 = last ? nA : cA + (size_t)(t + 2) * kstep; const char* b2 = last ? nB : cB + (size_t)(t + 2) * kstep;
;             const char* a3 = a2 + kstep; const char* b3 = b2 + kstep;
;             if (last && has_next) S.a_ready(nxt);
;             if constexpr (SP2) {
;             PG8_LDB(B0, 0, 0); PG8_LDB(B1, 0, 1); PG8_SCHED; PG8_LDA(At, 0, 0); PG8_STAGE(PG8_SA(1, 1), a1 + hstep, voffA);
;             PG8_WAIT_V(8); PG8_WAIT_L(0); PG8_BAR; PG8_MMA(0, 0, At, B0); PG8_MMA(0, 1, At, B1); PG8_BAR; PG8_SCHED;
;             PG8_LDA(At, 0, 1); PG8_STAGE(PG8_SB(0, 0), b2, voffB); PG8_STAGE(PG8_SB(0, 1), b2 + hstep, voffB); PG8_STAGE(PG8_SA(0, 0), a2, voffA);
;             PG8_WAIT_V(8); PG8_WAIT_L(0); PG8_BAR; PG8_MMA(1, 0, At, B0); PG8_MMA(1, 1, At, B1); PG8_BAR; PG8_SCHED;
.LBB0_826:
	s_add_u32 s16, s4, s14
	s_addc_u32 s17, s5, s15
	s_add_u32 s16, s16, 0x100
	s_addc_u32 s17, s17, 0
	s_add_u32 s48, s41, s14
	s_addc_u32 s49, s42, s15
	s_add_i32 s50, 0, 0x10000
	s_cmpk_eq_i32 s14, 0xf00
	s_cselect_b32 s19, s9, s17
	s_cselect_b32 s18, s43, s16
	v_add_u32_e32 v160, s50, v144
	s_cselect_b32 s17, s7, s49
	s_cselect_b32 s16, s46, s48
	s_add_i32 s51, 0, 0x14000
	ds_read_b128 v[146:149], v160
	ds_read_b128 v[150:153], v160 offset:1024
	ds_read_b128 v[156:159], v160 offset:2048
	ds_read_b128 v[180:183], v160 offset:3072
	v_add_u32_e32 v160, s51, v144
	ds_read_b128 v[200:203], v160
	ds_read_b128 v[204:207], v160 offset:1024
	ds_read_b128 v[208:211], v160 offset:2048
	ds_read_b128 v[212:215], v160 offset:3072
	v_lshl_add_u64 v[160:161], v[140:141], 0, s[14:15]
	s_add_i32 m0, s30, 0xc000
	ds_read_b128 v[216:219], v145
	ds_read_b128 v[220:223], v145 offset:1024
	ds_read_b128 v[224:227], v145 offset:2048
	ds_read_b128 v[228:231], v145 offset:3072
	ds_read_b128 v[232:235], v145 offset:4096
	ds_read_b128 v[236:239], v145 offset:5120
	ds_read_b128 v[240:243], v145 offset:6144
	ds_read_b128 v[244:247], v145 offset:7168
	global_load_lds_dwordx4 v[160:161], off
	v_lshl_add_u64 v[160:161], v[142:143], 0, s[14:15]
	s_add_i32 m0, s30, 0xe000
	s_nop 0
	global_load_lds_dwordx4 v[160:161], off
	s_waitcnt vmcnt(8)
	s_waitcnt lgkmcnt(0)
	s_setprio 1
	s_barrier
	v_mfma_f32_16x16x32_bf16 v[126:129], v[146:149], v[216:219], v[126:129]
	v_mfma_f32_16x16x32_bf16 v[122:125], v[156:159], v[216:219], v[122:125]
	v_mfma_f32_16x16x32_bf16 v[110:113], v[146:149], v[224:227], v[110:113]
	v_mfma_f32_16x16x32_bf16 v[106:109], v[156:159], v[224:227], v[106:109]
	v_mfma_f32_16x16x32_bf16 v[94:97], v[146:149], v[232:235], v[94:97]
	v_mfma_f32_16x16x32_bf16 v[90:93], v[156:159], v[232:235], v[90:93]
	v_mfma_f32_16x16x32_bf16 v[78:81], v[146:149], v[240:243], v[78:81]
	v_mfma_f32_16x16x32_bf16 v[74:77], v[156:159], v[240:243], v[74:77]
	v_mfma_f32_16x16x32_bf16 v[126:129], v[150:153], v[220:223], v[126:129]
	v_mfma_f32_16x16x32_bf16 v[122:125], v[180:183], v[220:223], v[122:125]
	v_mfma_f32_16x16x32_bf16 v[110:113], v[150:153], v[228:231], v[110:113]
	v_mfma_f32_16x16x32_bf16 v[106:109], v[180:183], v[228:231], v[106:109]
	v_mfma_f32_16x16x32_bf16 v[94:97], v[150:153], v[236:239], v[94:97]
	v_mfma_f32_16x16x32_bf16 v[90:93], v[180:183], v[236:239], v[90:93]
	v_mfma_f32_16x16x32_bf16 v[78:81], v[150:153], v[244:247], v[78:81]
	v_mfma_f32_16x16x32_bf16 v[74:77], v[180:183], v[244:247], v[74:77]
	v_mfma_f32_16x16x32_bf16 v[118:121], v[200:203], v[216:219], v[118:121]
	v_mfma_f32_16x16x32_bf16 v[114:117], v[208:211], v[216:219], v[114:117]
	v_mfma_f32_16x16x32_bf16 v[102:105], v[200:203], v[224:227], v[102:105]
	v_mfma_f32_16x16x32_bf16 v[98:101], v[208:211], v[224:227], v[98:101]
	v_mfma_f32_16x16x32_bf16 v[86:89], v[200:203], v[232:235], v[86:89]
	v_mfma_f32_16x16x32_bf16 v[82:85], v[208:211], v[232:235], v[82:85]
	v_mfma_f32_16x16x32_bf16 v[70:73], v[200:203], v[240:243], v[70:73]
	v_mfma_f32_16x16x32_bf16 v[66:69], v[208:211], v[240:243], v[66:69]
	v_mfma_f32_16x16x32_bf16 v[118:121], v[204:207], v[220:223], v[118:121]
	v_mfma_f32_16x16x32_bf16 v[114:117], v[212:215], v[220:223], v[114:117]
	v_mfma_f32_16x16x32_bf16 v[102:105], v[204:207], v[228:231], v[102:105]
	v_mfma_f32_16x16x32_bf16 v[98:101], v[212:215], v[228:231], v[98:101]
	v_mfma_f32_16x16x32_bf16 v[86:89], v[204:207], v[236:239], v[86:89]
	v_mfma_f32_16x16x32_bf16 v[82:85], v[212:215], v[236:239], v[82:85]
	v_mfma_f32_16x16x32_bf16 v[70:73], v[204:207], v[244:247], v[70:73]
	v_mfma_f32_16x16x32_bf16 v[66:69], v[212:215], v[244:247], v[66:69]
	s_barrier
	s_setprio 0
	s_add_i32 s48, s50, s29
	v_lshl_add_u64 v[160:161], s[16:17], 0, v[0:1]
	s_mov_b32 m0, s48
	ds_read_b128 v[216:219], v145 offset:16384
	ds_read_b128 v[220:223], v145 offset:17408
	ds_read_b128 v[224:227], v145 offset:18432
	ds_read_b128 v[228:231], v145 offset:19456
	ds_read_b128 v[232:235], v145 offset:20480
	ds_read_b128 v[236:239], v145 offset:21504
	ds_read_b128 v[240:243], v145 offset:22528
	ds_read_b128 v[244:247], v145 offset:23552
	global_load_lds_dwordx4 v[160:161], off
	s_add_i32 m0, s48, 0x2000
	s_add_u32 s48, s16, 0x80000
	v_lshl_add_u64 v[164:165], s[16:17], 0, v[130:131]
	s_addc_u32 s49, s17, 0
	s_add_i32 s50, s51, s29
	global_load_lds_dwordx4 v[164:165], off
	v_lshl_add_u64 v[166:167], s[48:49], 0, v[0:1]
	s_mov_b32 m0, s50
	v_lshl_add_u64 v[172:173], s[18:19], 0, v[132:133]
	global_load_lds_dwordx4 v[166:167], off
	v_lshl_add_u64 v[166:167], s[48:49], 0, v[130:131]
	s_add_i32 m0, s50, 0x2000
	s_nop 0
	global_load_lds_dwordx4 v[166:167], off
	v_lshl_add_u64 v[166:167], s[18:19], 0, v[134:135]
	s_mov_b32 m0, s30
	s_nop 0
	global_load_lds_dwordx4 v[166:167], off
	s_mov_b32 m0, s31
	s_nop 0
	global_load_lds_dwordx4 v[172:173], off
	s_waitcnt vmcnt(8)
	s_waitcnt lgkmcnt(0)
	s_setprio 1
	s_barrier
; #define PG8_STAGE(bufoff, gbase, voff) do { _Pragma("unroll") for (int _i = 0; _i < 2; ++_i) \
;         __builtin_amdgcn_global_load_lds((const unsigned*)((const char*)(gbase) + (voff)[_i]), (PG8_LAS unsigned*)(lds + (bufoff) + ldsw + _i * 8192), 16, 0, 0); } while (0)
; #define PG8_LDA(dst, b, h) do { _Pragma("unroll") for (int m = 0; m < 4; ++m) _Pragma("unroll") for (int k = 0; k < 2; ++k) dst[m][k] = *(const PG8_LAS bf16x8*)(lds + PG8_SA(b, h) + aoff + m * 2048 + k * 1024); } while (0)
; #define PG8_LDB(dst, b, h) do { _Pragma("unroll") for (int n = 0; n < 2; ++n) _Pragma("unroll") for (int k = 0; k < 2; ++k) dst[n][k] = *(const PG8_LAS bf16x8*)(lds + PG8_SB(b, h) + boff + n * 2048 + k * 1024); } while (0)
; #define PG8_MMA(ai, bj, At, Bt) do { __builtin_amdgcn_s_setprio(1); _Pragma("unroll") for (int m = 0; m < 4; ++m) _Pragma("unroll") for (int n = 0; n < 2; ++n) _Pragma("unroll") for (int k = 0; k < 2; ++k) \
;         acc[ai][bj][m][n] = __builtin_amdgcn_mfma_f32_16x16x32_bf16(Bt[n][k], At[m][k], acc[ai][bj][m][n], 0, 0, 0); __builtin_amdgcn_s_setprio(0); } while (0)
; #define PG8_WAIT_V(n) asm volatile("s_waitcnt vmcnt(" #n ")" ::: "memory")
; #define PG8_WAIT_L(n) asm volatile("s_waitcnt lgkmcnt(" #n ")" ::: "memory")
; #define PG8_BAR __builtin_amdgcn_s_barrier()
; #define PG8_SCHED __builtin_amdgcn_sched_barrier(0)
; template <class Epi, class Sched, bool ALIGN_EPI = false, bool SP2 = false>
; __device__ __forceinline__ void gemm_phase(PG8_LAS unsigned char* lds, const Gemm g, const Sched& S, const Epi& E) {
;     ...
;             PG8_WAIT_V(8); PG8_WAIT_L(0); PG8_BAR; PG8_MMA(1, 0, At, B0); PG8_MMA(1, 1, At, B1); PG8_BAR; PG8_SCHED;
;             PG8_LDB(B0, 1, 0); PG8_LDB(B1, 1, 1); PG8_SCHED; PG8_LDA(At, 1, 0); PG8_STAGE(PG8_SA(0, 1), a2 + hstep, voffA);
;             PG8_WAIT_V(8); PG8_WAIT_L(0); PG8_BAR; PG8_MMA(0, 0, At, B0); PG8_MMA(0, 1, At, B1); PG8_BAR; PG8_SCHED;
	v_mfma_f32_16x16x32_bf16 v[62:65], v[146:149], v[216:219], v[62:65]
	v_mfma_f32_16x16x32_bf16 v[58:61], v[156:159], v[216:219], v[58:61]
	v_mfma_f32_16x16x32_bf16 v[46:49], v[146:149], v[224:227], v[46:49]
	v_mfma_f32_16x16x32_bf16 v[42:45], v[156:159], v[224:227], v[42:45]
	v_mfma_f32_16x16x32_bf16 v[30:33], v[146:149], v[232:235], v[30:33]
	v_mfma_f32_16x16x32_bf16 v[26:29], v[156:159], v[232:235], v[26:29]
	v_mfma_f32_16x16x32_bf16 v[14:17], v[146:149], v[240:243], v[14:17]
	v_mfma_f32_16x16x32_bf16 v[10:13], v[156:159], v[240:243], v[10:13]
	v_mfma_f32_16x16x32_bf16 v[62:65], v[150:153], v[220:223], v[62:65]
	v_mfma_f32_16x16x32_bf16 v[58:61], v[180:183], v[220:223], v[58:61]
	v_mfma_f32_16x16x32_bf16 v[46:49], v[150:153], v[228:231], v[46:49]
	v_mfma_f32_16x16x32_bf16 v[42:45], v[180:183], v[228:231], v[42:45]
	v_mfma_f32_16x16x32_bf16 v[30:33], v[150:153], v[236:239], v[30:33]
	v_mfma_f32_16x16x32_bf16 v[26:29], v[180:183], v[236:239], v[26:29]
	v_mfma_f32_16x16x32_bf16 v[14:17], v[150:153], v[244:247], v[14:17]
	v_mfma_f32_16x16x32_bf16 v[10:13], v[180:183], v[244:247], v[10:13]
	v_mfma_f32_16x16x32_bf16 v[54:57], v[200:203], v[216:219], v[54:57]
	v_mfma_f32_16x16x32_bf16 v[50:53], v[208:211], v[216:219], v[50:53]
	v_mfma_f32_16x16x32_bf16 v[38:41], v[200:203], v[224:227], v[38:41]
	v_mfma_f32_16x16x32_bf16 v[34:37], v[208:211], v[224:227], v[34:37]
	v_mfma_f32_16x16x32_bf16 v[22:25], v[200:203], v[232:235], v[22:25]
	v_mfma_f32_16x16x32_bf16 v[18:21], v[208:211], v[232:235], v[18:21]
	v_mfma_f32_16x16x32_bf16 v[6:9], v[200:203], v[240:243], v[6:9]
	v_mfma_f32_16x16x32_bf16 v[2:5], v[208:211], v[240:243], v[2:5]
	v_mfma_f32_16x16x32_bf16 v[54:57], v[204:207], v[220:223], v[54:57]
	v_mfma_f32_16x16x32_bf16 v[50:53], v[212:215], v[220:223], v[50:53]
	v_mfma_f32_16x16x32_bf16 v[38:41], v[204:207], v[228:231], v[38:41]
	v_mfma_f32_16x16x32_bf16 v[34:37], v[212:215], v[228:231], v[34:37]
	v_mfma_f32_16x16x32_bf16 v[22:25], v[204:207], v[236:239], v[22:25]
	v_mfma_f32_16x16x32_bf16 v[18:21], v[212:215], v[236:239], v[18:21]
	v_mfma_f32_16x16x32_bf16 v[6:9], v[204:207], v[244:247], v[6:9]
	v_mfma_f32_16x16x32_bf16 v[2:5], v[212:215], v[244:247], v[2:5]
	s_barrier
	s_setprio 0
	s_add_i32 s48, 0, 0x18000
	v_add_u32_e32 v162, s48, v144
	s_add_i32 s49, 0, 0x1c000
	ds_read_b128 v[146:149], v162
	ds_read_b128 v[150:153], v162 offset:1024
	ds_read_b128 v[156:159], v162 offset:2048
	ds_read_b128 v[180:183], v162 offset:3072
	v_add_u32_e32 v162, s49, v144
	ds_read_b128 v[200:203], v162
	ds_read_b128 v[204:207], v162 offset:1024
	ds_read_b128 v[208:211], v162 offset:2048
	ds_read_b128 v[212:215], v162 offset:3072
	s_add_u32 s18, s18, 0x80000
	s_addc_u32 s19, s19, 0
	s_mov_b32 m0, s33
	v_lshl_add_u64 v[174:175], s[18:19], 0, v[134:135]
	ds_read_b128 v[216:219], v145 offset:32768
	ds_read_b128 v[220:223], v145 offset:33792
	ds_read_b128 v[224:227], v145 offset:34816
	ds_read_b128 v[228:231], v145 offset:35840
	ds_read_b128 v[232:235], v145 offset:36864
	ds_read_b128 v[236:239], v145 offset:37888
	ds_read_b128 v[240:243], v145 offset:38912
	ds_read_b128 v[244:247], v145 offset:39936
	global_load_lds_dwordx4 v[174:175], off
	v_lshl_add_u64 v[174:175], s[18:19], 0, v[132:133]
	s_mov_b32 m0, s34
	s_nop 0
	global_load_lds_dwordx4 v[174:175], off
	s_waitcnt vmcnt(8)
	s_waitcnt lgkmcnt(0)
	s_setprio 1
	s_barrier
	v_mfma_f32_16x16x32_bf16 v[126:129], v[146:149], v[216:219], v[126:129]
	v_mfma_f32_16x16x32_bf16 v[122:125], v[156:159], v[216:219], v[122:125]
	v_mfma_f32_16x16x32_bf16 v[110:113], v[146:149], v[224:227], v[110:113]
	v_mfma_f32_16x16x32_bf16 v[106:109], v[156:159], v[224:227], v[106:109]
	v_mfma_f32_16x16x32_bf16 v[94:97], v[146:149], v[232:235], v[94:97]
	v_mfma_f32_16x16x32_bf16 v[90:93], v[156:159], v[232:235], v[90:93]
	v_mfma_f32_16x16x32_bf16 v[78:81], v[146:149], v[240:243], v[78:81]
	v_mfma_f32_16x16x32_bf16 v[74:77], v[156:159], v[240:243], v[74:77]
	v_mfma_f32_16x16x32_bf16 v[126:129], v[150:153], v[220:223], v[126:129]
	v_mfma_f32_16x16x32_bf16 v[122:125], v[180:183], v[220:223], v[122:125]
	v_mfma_f32_16x16x32_bf16 v[110:113], v[150:153], v[228:231], v[110:113]
	v_mfma_f32_16x16x32_bf16 v[106:109], v[180:183], v[228:231], v[106:109]
	v_mfma_f32_16x16x32_bf16 v[94:97], v[150:153], v[236:239], v[94:97]
	v_mfma_f32_16x16x32_bf16 v[90:93], v[180:183], v[236:239], v[90:93]
	v_mfma_f32_16x16x32_bf16 v[78:81], v[150:153], v[244:247], v[78:81]
	v_mfma_f32_16x16x32_bf16 v[74:77], v[180:183], v[244:247], v[74:77]
	v_mfma_f32_16x16x32_bf16 v[118:121], v[200:203], v[216:219], v[118:121]
	v_mfma_f32_16x16x32_bf16 v[114:117], v[208:211], v[216:219], v[114:117]
	v_mfma_f32_16x16x32_bf16 v[102:105], v[200:203], v[224:227], v[102:105]
	v_mfma_f32_16x16x32_bf16 v[98:101], v[208:211], v[224:227], v[98:101]
	v_mfma_f32_16x16x32_bf16 v[86:89], v[200:203], v[232:235], v[86:89]
	v_mfma_f32_16x16x32_bf16 v[82:85], v[208:211], v[232:235], v[82:85]
	v_mfma_f32_16x16x32_bf16 v[70:73], v[200:203], v[240:243], v[70:73]
	v_mfma_f32_16x16x32_bf16 v[66:69], v[208:211], v[240:243], v[66:69]
	v_mfma_f32_16x16x32_bf16 v[118:121], v[204:207], v[220:223], v[118:121]
	v_mfma_f32_16x16x32_bf16 v[114:117], v[212:215], v[220:223], v[114:117]
	v_mfma_f32_16x16x32_bf16 v[102:105], v[204:207], v[228:231], v[102:105]
	v_mfma_f32_16x16x32_bf16 v[98:101], v[212:215], v[228:231], v[98:101]
	v_mfma_f32_16x16x32_bf16 v[86:89], v[204:207], v[236:239], v[86:89]
	v_mfma_f32_16x16x32_bf16 v[82:85], v[212:215], v[236:239], v[82:85]
	v_mfma_f32_16x16x32_bf16 v[70:73], v[204:207], v[244:247], v[70:73]
	v_mfma_f32_16x16x32_bf16 v[66:69], v[212:215], v[244:247], v[66:69]
	s_barrier
; #define PG8_WAIT_V(n) asm volatile("s_waitcnt vmcnt(" #n ")" ::: "memory")
; #define PG8_BAR __builtin_amdgcn_s_barrier()
; template <class Epi, class Sched, bool ALIGN_EPI = false, bool SP2 = false>
; __device__ __forceinline__ void gemm_phase(PG8_LAS unsigned char* lds, const Gemm g, const Sched& S, const Epi& E) {
;     ...
;             PG8_LDA(At, 1, 1); PG8_STAGE(PG8_SB(1, 0), b3, voffB); PG8_STAGE(PG8_SB(1, 1), b3 + hstep, voffB); PG8_STAGE(PG8_SA(1, 0), a3, voffA);
;             PG8_WAIT_V(8); PG8_WAIT_L(0); PG8_BAR; PG8_MMA(1, 0, At, B0); PG8_MMA(1, 1, At, B1); PG8_BAR; PG8_SCHED;
;             } else {
;             PG8_LDB(B0, 0, 0); PG8_SCHED; PG8_LDA(At, 0, 0); PG8_STAGE(PG8_SA(1, 1), a1 + hstep, voffA);
;             PG8_WAIT_L(8); PG8_BAR; PG8_WAIT_L(0); PG8_MMA(0, 0, At, B0); PG8_BAR; PG8_SCHED;
;             PG8_LDB(B1, 0, 1); PG8_STAGE(PG8_SB(0, 0), b2, voffB);
;             PG8_BAR; PG8_WAIT_L(0); PG8_MMA(0, 1, At, B1); PG8_BAR;
;             PG8_LDA(At, 0, 1); PG8_STAGE(PG8_SA(0, 0), a2, voffA);
;             PG8_BAR; PG8_WAIT_L(0); PG8_MMA(1, 0, At, B0); PG8_BAR; PG8_SCHED;
;             PG8_STAGE(PG8_SB(0, 1), b2 + hstep, voffB);
;             PG8_WAIT_V(6); PG8_BAR; PG8_MMA(1, 1, At, B1); PG8_BAR;
;             PG8_LDB(B0, 1, 0); PG8_SCHED; PG8_LDA(At, 1, 0); PG8_STAGE(PG8_SA(0, 1), a2 + hstep, voffA);
;             PG8_WAIT_L(8); PG8_BAR; PG8_WAIT_L(0); PG8_MMA(0, 0, At, B0); PG8_BAR; PG8_SCHED;
;             PG8_LDB(B1, 1, 1); PG8_STAGE(PG8_SB(1, 0), b3, voffB);
;             PG8_BAR; PG8_WAIT_L(0); PG8_MMA(0, 1, At, B1); PG8_BAR;
;             PG8_LDA(At, 1, 1); PG8_STAGE(PG8_SA(1, 0), a3, voffA);
;             PG8_BAR; PG8_WAIT_L(0); PG8_MMA(1, 0, At, B0); PG8_BAR; PG8_SCHED;
;             PG8_STAGE(PG8_SB(1, 1), b3 + hstep, voffB);
;             PG8_WAIT_V(6); PG8_BAR; PG8_MMA(1, 1, At, B1); PG8_BAR;
;             }
;         }
;         if constexpr (ALIGN_EPI) { if (wr == 0) PG8_BAR; }
;         if constexpr (!Epi::AFTER_DRAIN) { E(acc, cur, wr, wc, fr, fq); S.done(cur); }
;         if (!has_next) break;
; #pragma unroll
;         for (int a = 0; a < 2; ++a)
; #pragma unroll
;             for (int b = 0; b < 2; ++b)
; #pragma unroll
;                 for (int m = 0; m < 4; ++m)
; #pragma unroll
;                     for (int n = 0; n < 2; ++n) acc[a][b][m][n] = (f32x4){0.f, 0.f, 0.f, 0.f};
;         cur = nxt; cA = nA; cB = nB; ++ui;
	s_setprio 0
	s_add_i32 s18, s48, s29
	v_lshl_add_u64 v[160:161], v[160:161], 0, s[44:45]
	s_mov_b32 m0, s18
	ds_read_b128 v[216:219], v145 offset:49152
	ds_read_b128 v[220:223], v145 offset:50176
	ds_read_b128 v[224:227], v145 offset:51200
	ds_read_b128 v[228:231], v145 offset:52224
	ds_read_b128 v[232:235], v145 offset:53248
	ds_read_b128 v[236:239], v145 offset:54272
	ds_read_b128 v[240:243], v145 offset:55296
	ds_read_b128 v[244:247], v145 offset:56320
	global_load_lds_dwordx4 v[160:161], off
	s_add_i32 m0, s18, 0x2000
	s_add_u32 s16, s16, 0x80080
	v_lshl_add_u64 v[160:161], v[164:165], 0, s[44:45]
	s_addc_u32 s17, s17, 0
	s_add_i32 s18, s49, s29
	global_load_lds_dwordx4 v[160:161], off
	v_lshl_add_u64 v[160:161], s[16:17], 0, v[0:1]
	s_mov_b32 m0, s18
	s_nop 0
	global_load_lds_dwordx4 v[160:161], off
	v_lshl_add_u64 v[160:161], s[16:17], 0, v[130:131]
	s_add_i32 m0, s18, 0x2000
	s_nop 0
	global_load_lds_dwordx4 v[160:161], off
	v_lshl_add_u64 v[160:161], v[166:167], 0, s[44:45]
	s_mov_b32 m0, s35
	s_nop 0
	global_load_lds_dwordx4 v[160:161], off
	v_lshl_add_u64 v[160:161], v[172:173], 0, s[44:45]
	s_mov_b32 m0, s36
	s_nop 0
	global_load_lds_dwordx4 v[160:161], off
	s_waitcnt vmcnt(8)
	s_waitcnt lgkmcnt(0)
	s_setprio 1
	s_barrier
	v_mfma_f32_16x16x32_bf16 v[62:65], v[146:149], v[216:219], v[62:65]
	v_mfma_f32_16x16x32_bf16 v[58:61], v[156:159], v[216:219], v[58:61]
	v_mfma_f32_16x16x32_bf16 v[46:49], v[146:149], v[224:227], v[46:49]
	v_mfma_f32_16x16x32_bf16 v[42:45], v[156:159], v[224:227], v[42:45]
	v_mfma_f32_16x16x32_bf16 v[30:33], v[146:149], v[232:235], v[30:33]
	v_mfma_f32_16x16x32_bf16 v[26:29], v[156:159], v[232:235], v[26:29]
	v_mfma_f32_16x16x32_bf16 v[14:17], v[146:149], v[240:243], v[14:17]
	v_mfma_f32_16x16x32_bf16 v[10:13], v[156:159], v[240:243], v[10:13]
	v_mfma_f32_16x16x32_bf16 v[62:65], v[150:153], v[220:223], v[62:65]
	v_mfma_f32_16x16x32_bf16 v[58:61], v[180:183], v[220:223], v[58:61]
	v_mfma_f32_16x16x32_bf16 v[46:49], v[150:153], v[228:231], v[46:49]
	v_mfma_f32_16x16x32_bf16 v[42:45], v[180:183], v[228:231], v[42:45]
	v_mfma_f32_16x16x32_bf16 v[30:33], v[150:153], v[236:239], v[30:33]
	v_mfma_f32_16x16x32_bf16 v[26:29], v[180:183], v[236:239], v[26:29]
	v_mfma_f32_16x16x32_bf16 v[14:17], v[150:153], v[244:247], v[14:17]
	v_mfma_f32_16x16x32_bf16 v[10:13], v[180:183], v[244:247], v[10:13]
	v_mfma_f32_16x16x32_bf16 v[54:57], v[200:203], v[216:219], v[54:57]
	v_mfma_f32_16x16x32_bf16 v[50:53], v[208:211], v[216:219], v[50:53]
	v_mfma_f32_16x16x32_bf16 v[38:41], v[200:203], v[224:227], v[38:41]
	v_mfma_f32_16x16x32_bf16 v[34:37], v[208:211], v[224:227], v[34:37]
	v_mfma_f32_16x16x32_bf16 v[22:25], v[200:203], v[232:235], v[22:25]
	v_mfma_f32_16x16x32_bf16 v[18:21], v[208:211], v[232:235], v[18:21]
	v_mfma_f32_16x16x32_bf16 v[6:9], v[200:203], v[240:243], v[6:9]
	v_mfma_f32_16x16x32_bf16 v[2:5], v[208:211], v[240:243], v[2:5]
	v_mfma_f32_16x16x32_bf16 v[54:57], v[204:207], v[220:223], v[54:57]
	v_mfma_f32_16x16x32_bf16 v[50:53], v[212:215], v[220:223], v[50:53]
	v_mfma_f32_16x16x32_bf16 v[38:41], v[204:207], v[228:231], v[38:41]
	v_mfma_f32_16x16x32_bf16 v[34:37], v[212:215], v[228:231], v[34:37]
	v_mfma_f32_16x16x32_bf16 v[22:25], v[204:207], v[236:239], v[22:25]
	v_mfma_f32_16x16x32_bf16 v[18:21], v[212:215], v[236:239], v[18:21]
	v_mfma_f32_16x16x32_bf16 v[6:9], v[204:207], v[244:247], v[6:9]
	v_mfma_f32_16x16x32_bf16 v[2:5], v[212:215], v[244:247], v[2:5]
	s_barrier
	s_setprio 0
	s_add_i32 s47, s47, 2
	s_add_u32 s14, s14, 0x100
	s_addc_u32 s15, s15, 0
	s_cmp_gt_u32 s47, 29
	s_cbranch_scc0 .LBB0_826
	s_add_u32 s14, s41, 0xffffff00
	s_addc_u32 s15, s42, -1
	s_andn2_b64 vcc, exec, s[2:3]
	s_cbranch_vccnz .LBB0_817
	v_mov_b32_e32 v2, 0
	s_mov_b32 s25, s6
	s_mov_b32 s24, s8
	s_mov_b64 s[4:5], s[12:13]
	s_mov_b32 s37, s40
	v_mov_b32_e32 v3, v2
	v_mov_b32_e32 v4, v2
	v_mov_b32_e32 v5, v2
	v_mov_b32_e32 v6, v2
	v_mov_b32_e32 v7, v2
	v_mov_b32_e32 v8, v2
	v_mov_b32_e32 v9, v2
	v_mov_b32_e32 v18, v2
	v_mov_b32_e32 v19, v2
	v_mov_b32_e32 v20, v2
	v_mov_b32_e32 v21, v2
	v_mov_b32_e32 v22, v2
	v_mov_b32_e32 v23, v2
	v_mov_b32_e32 v24, v2
	v_mov_b32_e32 v25, v2
	v_mov_b32_e32 v34, v2
	v_mov_b32_e32 v35, v2
	v_mov_b32_e32 v36, v2
	v_mov_b32_e32 v37, v2
	v_mov_b32_e32 v38, v2
	v_mov_b32_e32 v39, v2
	v_mov_b32_e32 v40, v2
	v_mov_b32_e32 v41, v2
	v_mov_b32_e32 v50, v2
	v_mov_b32_e32 v51, v2
	v_mov_b32_e32 v52, v2
	v_mov_b32_e32 v53, v2
	v_mov_b32_e32 v54, v2
	v_mov_b32_e32 v55, v2
	v_mov_b32_e32 v56, v2
	v_mov_b32_e32 v57, v2
	v_mov_b32_e32 v10, v2
	v_mov_b32_e32 v11, v2
	v_mov_b32_e32 v12, v2
	v_mov_b32_e32 v13, v2
	v_mov_b32_e32 v14, v2
	v_mov_b32_e32 v15, v2
	v_mov_b32_e32 v16, v2
	v_mov_b32_e32 v17, v2
	v_mov_b32_e32 v26, v2
	v_mov_b32_e32 v27, v2
	v_mov_b32_e32 v28, v2
	v_mov_b32_e32 v29, v2
	v_mov_b32_e32 v30, v2
	v_mov_b32_e32 v31, v2
	v_mov_b32_e32 v32, v2
	v_mov_b32_e32 v33, v2
	v_mov_b32_e32 v42, v2
	v_mov_b32_e32 v43, v2
	v_mov_b32_e32 v44, v2
	v_mov_b32_e32 v45, v2
	v_mov_b32_e32 v46, v2
	v_mov_b32_e32 v47, v2
	v_mov_b32_e32 v48, v2
	v_mov_b32_e32 v49, v2
	v_mov_b32_e32 v58, v2
	v_mov_b32_e32 v59, v2
	v_mov_b32_e32 v60, v2
	v_mov_b32_e32 v61, v2
	v_mov_b32_e32 v62, v2
	v_mov_b32_e32 v63, v2
	v_mov_b32_e32 v64, v2
	v_mov_b32_e32 v65, v2
	v_mov_b32_e32 v66, v2
	v_mov_b32_e32 v67, v2
	v_mov_b32_e32 v68, v2
	v_mov_b32_e32 v69, v2
	v_mov_b32_e32 v70, v2
	v_mov_b32_e32 v71, v2
	v_mov_b32_e32 v72, v2
	v_mov_b32_e32 v73, v2
	v_mov_b32_e32 v82, v2
	v_mov_b32_e32 v83, v2
	v_mov_b32_e32 v84, v2
	v_mov_b32_e32 v85, v2
	v_mov_b32_e32 v86, v2
	v_mov_b32_e32 v87, v2
	v_mov_b32_e32 v88, v2
	v_mov_b32_e32 v89, v2
	v_mov_b32_e32 v98, v2
	v_mov_b32_e32 v99, v2
	v_mov_b32_e32 v100, v2
	v_mov_b32_e32 v101, v2
	v_mov_b32_e32 v102, v2
	v_mov_b32_e32 v103, v2
	v_mov_b32_e32 v104, v2
	v_mov_b32_e32 v105, v2
	v_mov_b32_e32 v114, v2
	v_mov_b32_e32 v115, v2
	v_mov_b32_e32 v116, v2
	v_mov_b32_e32 v117, v2
	v_mov_b32_e32 v118, v2
	v_mov_b32_e32 v119, v2
	v_mov_b32_e32 v120, v2
	v_mov_b32_e32 v121, v2
	v_mov_b32_e32 v74, v2
	v_mov_b32_e32 v75, v2
	v_mov_b32_e32 v76, v2
	v_mov_b32_e32 v77, v2
	v_mov_b32_e32 v78, v2
	v_mov_b32_e32 v79, v2
	v_mov_b32_e32 v80, v2
	v_mov_b32_e32 v81, v2
	v_mov_b32_e32 v90, v2
	v_mov_b32_e32 v91, v2
	v_mov_b32_e32 v92, v2
	v_mov_b32_e32 v93, v2
	v_mov_b32_e32 v94, v2
	v_mov_b32_e32 v95, v2
	v_mov_b32_e32 v96, v2
	v_mov_b32_e32 v97, v2
	v_mov_b32_e32 v106, v2
	v_mov_b32_e32 v107, v2
	v_mov_b32_e32 v108, v2
	v_mov_b32_e32 v109, v2
	v_mov_b32_e32 v110, v2
	v_mov_b32_e32 v111, v2
	v_mov_b32_e32 v112, v2
	v_mov_b32_e32 v113, v2
	v_mov_b32_e32 v122, v2
	v_mov_b32_e32 v123, v2
	v_mov_b32_e32 v124, v2
	v_mov_b32_e32 v125, v2
	v_mov_b32_e32 v126, v2
	v_mov_b32_e32 v127, v2
	v_mov_b32_e32 v128, v2
	v_mov_b32_e32 v129, v2
	s_andn2_b64 vcc, exec, s[0:1]
	s_cbranch_vccnz .LBB0_818

; #define PG8_STAGE(bufoff, gbase, voff) do { _Pragma("unroll") for (int _i = 0; _i < 2; ++_i) \
;         __builtin_amdgcn_global_load_lds((const unsigned*)((const char*)(gbase) + (voff)[_i]), (PG8_LAS unsigned*)(lds + (bufoff) + ldsw + _i * 8192), 16, 0, 0); } while (0)
; #define PG8_LDA(dst, b, h) do { _Pragma("unroll") for (int m = 0; m < 4; ++m) _Pragma("unroll") for (int k = 0; k < 2; ++k) dst[m][k] = *(const PG8_LAS bf16x8*)(lds + PG8_SA(b, h) + aoff + m * 2048 + k * 1024); } while (0)
; #define PG8_LDB(dst, b, h) do { _Pragma("unroll") for (int n = 0; n < 2; ++n) _Pragma("unroll") for (int k = 0; k < 2; ++k) dst[n][k] = *(const PG8_LAS bf16x8*)(lds + PG8_SB(b, h) + boff + n * 2048 + k * 1024); } while (0)
; #define PG8_MMA(ai, bj, At, Bt) do { __builtin_amdgcn_s_setprio(1); _Pragma("unroll") for (int m = 0; m < 4; ++m) _Pragma("unroll") for (int n = 0; n < 2; ++n) _Pragma("unroll") for (int k = 0; k < 2; ++k) \
;         acc[ai][bj][m][n] = __builtin_amdgcn_mfma_f32_16x16x32_bf16(Bt[n][k], At[m][k], acc[ai][bj][m][n], 0, 0, 0); __builtin_amdgcn_s_setprio(0); } while (0)
; #define PG8_WAIT_V(n) asm volatile("s_waitcnt vmcnt(" #n ")" ::: "memory")
; #define PG8_WAIT_L(n) asm volatile("s_waitcnt lgkmcnt(" #n ")" ::: "memory")
; template <class Epi, class Sched, bool ALIGN_EPI = false, bool SP2 = false>
; __device__ __forceinline__ void gemm_phase(PG8_LAS unsigned char* lds, const Gemm g, const Sched& S, const Epi& E) {
;     ...
;             const bool last = (t == nt - 2);
;             const char* a1 = cA + (size_t)(t + 1) * kstep;
;             const char* a2 = last ? nA : cA + (size_t)(t + 2) * kstep; const char* b2 = last ? nB : cB + (size_t)(t + 2) * kstep;
;             const char* a3 = a2 + kstep; const char* b3 = b2 + kstep;
;             if (last && has_next) S.a_ready(nxt);
;             if constexpr (SP2) {
;             PG8_LDB(B0, 0, 0); PG8_LDB(B1, 0, 1); PG8_SCHED; PG8_LDA(At, 0, 0); PG8_STAGE(PG8_SA(1, 1), a1 + hstep, voffA);
;             PG8_WAIT_V(8); PG8_WAIT_L(0); PG8_BAR; PG8_MMA(0, 0, At, B0); PG8_MMA(0, 1, At, B1); PG8_BAR; PG8_SCHED;
;             PG8_LDA(At, 0, 1); PG8_STAGE(PG8_SB(0, 0), b2, voffB); PG8_STAGE(PG8_SB(0, 1), b2 + hstep, voffB); PG8_STAGE(PG8_SA(0, 0), a2, voffA);
;             PG8_WAIT_V(8); PG8_WAIT_L(0); PG8_BAR; PG8_MMA(1, 0, At, B0); PG8_MMA(1, 1, At, B1); PG8_BAR; PG8_SCHED;
.LBB0_966:
	s_add_u32 s16, s14, 0xfff80080
	s_addc_u32 s17, s15, -1
	s_add_i32 s40, 0, 0x10000
	s_cmp_eq_u32 s37, 28
	s_cselect_b32 s19, s9, s17
	s_cselect_b32 s18, s33, s16
	s_cselect_b32 s17, s7, s36
	s_cselect_b32 s16, s34, s35
	s_add_i32 s42, 0, 0x14000
	v_add_u32_e32 v156, s40, v145
	v_add_u32_e32 v160, s42, v145
	ds_read_b128 v[140:143], v156
	ds_read_b128 v[148:151], v156 offset:1024
	ds_read_b128 v[152:155], v156 offset:2048
	ds_read_b128 v[156:159], v156 offset:3072
	ds_read_b128 v[164:167], v160
	ds_read_b128 v[172:175], v160 offset:1024
	ds_read_b128 v[176:179], v160 offset:2048
	ds_read_b128 v[180:183], v160 offset:3072
	v_lshl_add_u64 v[160:161], s[14:15], 0, v[136:137]
	s_add_i32 m0, s23, 0xc000
	ds_read_b128 v[200:203], v147
	ds_read_b128 v[204:207], v147 offset:1024
	ds_read_b128 v[208:211], v147 offset:2048
	ds_read_b128 v[212:215], v147 offset:3072
	ds_read_b128 v[216:219], v147 offset:4096
	ds_read_b128 v[220:223], v147 offset:5120
	ds_read_b128 v[224:227], v147 offset:6144
	ds_read_b128 v[228:231], v147 offset:7168
	global_load_lds_dwordx4 v[160:161], off
	v_lshl_add_u64 v[160:161], s[14:15], 0, v[138:139]
	s_add_i32 m0, s23, 0xe000
	s_nop 0
	global_load_lds_dwordx4 v[160:161], off
	s_waitcnt vmcnt(8)
	s_waitcnt lgkmcnt(0)
	s_setprio 1
	s_barrier
	v_mfma_f32_16x16x32_bf16 v[126:129], v[140:143], v[200:203], v[126:129]
	v_mfma_f32_16x16x32_bf16 v[118:121], v[152:155], v[200:203], v[118:121]
	v_mfma_f32_16x16x32_bf16 v[110:113], v[140:143], v[208:211], v[110:113]
	v_mfma_f32_16x16x32_bf16 v[102:105], v[152:155], v[208:211], v[102:105]
	v_mfma_f32_16x16x32_bf16 v[94:97], v[140:143], v[216:219], v[94:97]
	v_mfma_f32_16x16x32_bf16 v[86:89], v[152:155], v[216:219], v[86:89]
	v_mfma_f32_16x16x32_bf16 v[78:81], v[140:143], v[224:227], v[78:81]
	v_mfma_f32_16x16x32_bf16 v[70:73], v[152:155], v[224:227], v[70:73]
	v_mfma_f32_16x16x32_bf16 v[126:129], v[148:151], v[204:207], v[126:129]
	v_mfma_f32_16x16x32_bf16 v[118:121], v[156:159], v[204:207], v[118:121]
	v_mfma_f32_16x16x32_bf16 v[110:113], v[148:151], v[212:215], v[110:113]
	v_mfma_f32_16x16x32_bf16 v[102:105], v[156:159], v[212:215], v[102:105]
	v_mfma_f32_16x16x32_bf16 v[94:97], v[148:151], v[220:223], v[94:97]
	v_mfma_f32_16x16x32_bf16 v[86:89], v[156:159], v[220:223], v[86:89]
	v_mfma_f32_16x16x32_bf16 v[78:81], v[148:151], v[228:231], v[78:81]
	v_mfma_f32_16x16x32_bf16 v[70:73], v[156:159], v[228:231], v[70:73]
	v_mfma_f32_16x16x32_bf16 v[122:125], v[164:167], v[200:203], v[122:125]
	v_mfma_f32_16x16x32_bf16 v[114:117], v[176:179], v[200:203], v[114:117]
	v_mfma_f32_16x16x32_bf16 v[106:109], v[164:167], v[208:211], v[106:109]
	v_mfma_f32_16x16x32_bf16 v[98:101], v[176:179], v[208:211], v[98:101]
	v_mfma_f32_16x16x32_bf16 v[90:93], v[164:167], v[216:219], v[90:93]
	v_mfma_f32_16x16x32_bf16 v[82:85], v[176:179], v[216:219], v[82:85]
	v_mfma_f32_16x16x32_bf16 v[74:77], v[164:167], v[224:227], v[74:77]
	v_mfma_f32_16x16x32_bf16 v[66:69], v[176:179], v[224:227], v[66:69]
	v_mfma_f32_16x16x32_bf16 v[122:125], v[172:175], v[204:207], v[122:125]
	v_mfma_f32_16x16x32_bf16 v[114:117], v[180:183], v[204:207], v[114:117]
	v_mfma_f32_16x16x32_bf16 v[106:109], v[172:175], v[212:215], v[106:109]
	v_mfma_f32_16x16x32_bf16 v[98:101], v[180:183], v[212:215], v[98:101]
	v_mfma_f32_16x16x32_bf16 v[90:93], v[172:175], v[220:223], v[90:93]
	v_mfma_f32_16x16x32_bf16 v[82:85], v[180:183], v[220:223], v[82:85]
	v_mfma_f32_16x16x32_bf16 v[74:77], v[172:175], v[228:231], v[74:77]
	v_mfma_f32_16x16x32_bf16 v[66:69], v[180:183], v[228:231], v[66:69]
	s_barrier
	s_setprio 0
	s_add_i32 s40, s40, s22
	v_lshl_add_u64 v[160:161], s[16:17], 0, v[0:1]
	s_mov_b32 m0, s40
	ds_read_b128 v[200:203], v147 offset:16384
	ds_read_b128 v[204:207], v147 offset:17408
	ds_read_b128 v[208:211], v147 offset:18432
	ds_read_b128 v[212:215], v147 offset:19456
	ds_read_b128 v[216:219], v147 offset:20480
	ds_read_b128 v[220:223], v147 offset:21504
	ds_read_b128 v[224:227], v147 offset:22528
	ds_read_b128 v[228:231], v147 offset:23552
	global_load_lds_dwordx4 v[160:161], off
	s_add_i32 m0, s40, 0x2000
	s_add_u32 s40, s16, 0x80000
	v_lshl_add_u64 v[184:185], s[16:17], 0, v[130:131]
	s_addc_u32 s41, s17, 0
	s_add_i32 s42, s42, s22
	global_load_lds_dwordx4 v[184:185], off
	v_lshl_add_u64 v[232:233], s[40:41], 0, v[0:1]
	s_mov_b32 m0, s42
	v_lshl_add_u64 v[234:235], s[18:19], 0, v[132:133]
	global_load_lds_dwordx4 v[232:233], off
	v_lshl_add_u64 v[232:233], s[40:41], 0, v[130:131]
	s_add_i32 m0, s42, 0x2000
	s_nop 0
	global_load_lds_dwordx4 v[232:233], off
	v_lshl_add_u64 v[232:233], s[18:19], 0, v[134:135]
	s_mov_b32 m0, s23
	s_nop 0
	global_load_lds_dwordx4 v[232:233], off
	s_mov_b32 m0, s24
	s_nop 0
	global_load_lds_dwordx4 v[234:235], off
	s_waitcnt vmcnt(8)
	s_waitcnt lgkmcnt(0)
	s_setprio 1
	s_barrier
; #define PG8_STAGE(bufoff, gbase, voff) do { _Pragma("unroll") for (int _i = 0; _i < 2; ++_i) \
;         __builtin_amdgcn_global_load_lds((const unsigned*)((const char*)(gbase) + (voff)[_i]), (PG8_LAS unsigned*)(lds + (bufoff) + ldsw + _i * 8192), 16, 0, 0); } while (0)
; #define PG8_LDA(dst, b, h) do { _Pragma("unroll") for (int m = 0; m < 4; ++m) _Pragma("unroll") for (int k = 0; k < 2; ++k) dst[m][k] = *(const PG8_LAS bf16x8*)(lds + PG8_SA(b, h) + aoff + m * 2048 + k * 1024); } while (0)
; #define PG8_LDB(dst, b, h) do { _Pragma("unroll") for (int n = 0; n < 2; ++n) _Pragma("unroll") for (int k = 0; k < 2; ++k) dst[n][k] = *(const PG8_LAS bf16x8*)(lds + PG8_SB(b, h) + boff + n * 2048 + k * 1024); } while (0)
; #define PG8_MMA(ai, bj, At, Bt) do { __builtin_amdgcn_s_setprio(1); _Pragma("unroll") for (int m = 0; m < 4; ++m) _Pragma("unroll") for (int n = 0; n < 2; ++n) _Pragma("unroll") for (int k = 0; k < 2; ++k) \
;         acc[ai][bj][m][n] = __builtin_amdgcn_mfma_f32_16x16x32_bf16(Bt[n][k], At[m][k], acc[ai][bj][m][n], 0, 0, 0); __builtin_amdgcn_s_setprio(0); } while (0)
; #define PG8_WAIT_V(n) asm volatile("s_waitcnt vmcnt(" #n ")" ::: "memory")
; #define PG8_WAIT_L(n) asm volatile("s_waitcnt lgkmcnt(" #n ")" ::: "memory")
; #define PG8_BAR __builtin_amdgcn_s_barrier()
; #define PG8_SCHED __builtin_amdgcn_sched_barrier(0)
; template <class Epi, class Sched, bool ALIGN_EPI = false, bool SP2 = false>
; __device__ __forceinline__ void gemm_phase(PG8_LAS unsigned char* lds, const Gemm g, const Sched& S, const Epi& E) {
;     ...
;             PG8_WAIT_V(8); PG8_WAIT_L(0); PG8_BAR; PG8_MMA(1, 0, At, B0); PG8_MMA(1, 1, At, B1); PG8_BAR; PG8_SCHED;
;             PG8_LDB(B0, 1, 0); PG8_LDB(B1, 1, 1); PG8_SCHED; PG8_LDA(At, 1, 0); PG8_STAGE(PG8_SA(0, 1), a2 + hstep, voffA);
;             PG8_WAIT_V(8); PG8_WAIT_L(0); PG8_BAR; PG8_MMA(0, 0, At, B0); PG8_MMA(0, 1, At, B1); PG8_BAR; PG8_SCHED;
	v_mfma_f32_16x16x32_bf16 v[62:65], v[140:143], v[200:203], v[62:65]
	v_mfma_f32_16x16x32_bf16 v[54:57], v[152:155], v[200:203], v[54:57]
	v_mfma_f32_16x16x32_bf16 v[46:49], v[140:143], v[208:211], v[46:49]
	v_mfma_f32_16x16x32_bf16 v[38:41], v[152:155], v[208:211], v[38:41]
	v_mfma_f32_16x16x32_bf16 v[30:33], v[140:143], v[216:219], v[30:33]
	v_mfma_f32_16x16x32_bf16 v[22:25], v[152:155], v[216:219], v[22:25]
	v_mfma_f32_16x16x32_bf16 v[14:17], v[140:143], v[224:227], v[14:17]
	v_mfma_f32_16x16x32_bf16 v[6:9], v[152:155], v[224:227], v[6:9]
	v_mfma_f32_16x16x32_bf16 v[62:65], v[148:151], v[204:207], v[62:65]
	v_mfma_f32_16x16x32_bf16 v[54:57], v[156:159], v[204:207], v[54:57]
	v_mfma_f32_16x16x32_bf16 v[46:49], v[148:151], v[212:215], v[46:49]
	v_mfma_f32_16x16x32_bf16 v[38:41], v[156:159], v[212:215], v[38:41]
	v_mfma_f32_16x16x32_bf16 v[30:33], v[148:151], v[220:223], v[30:33]
	v_mfma_f32_16x16x32_bf16 v[22:25], v[156:159], v[220:223], v[22:25]
	v_mfma_f32_16x16x32_bf16 v[14:17], v[148:151], v[228:231], v[14:17]
	v_mfma_f32_16x16x32_bf16 v[6:9], v[156:159], v[228:231], v[6:9]
	v_mfma_f32_16x16x32_bf16 v[58:61], v[164:167], v[200:203], v[58:61]
	v_mfma_f32_16x16x32_bf16 v[50:53], v[176:179], v[200:203], v[50:53]
	v_mfma_f32_16x16x32_bf16 v[42:45], v[164:167], v[208:211], v[42:45]
	v_mfma_f32_16x16x32_bf16 v[34:37], v[176:179], v[208:211], v[34:37]
	v_mfma_f32_16x16x32_bf16 v[26:29], v[164:167], v[216:219], v[26:29]
	v_mfma_f32_16x16x32_bf16 v[18:21], v[176:179], v[216:219], v[18:21]
	v_mfma_f32_16x16x32_bf16 v[10:13], v[164:167], v[224:227], v[10:13]
	v_mfma_f32_16x16x32_bf16 v[2:5], v[176:179], v[224:227], v[2:5]
	v_mfma_f32_16x16x32_bf16 v[58:61], v[172:175], v[204:207], v[58:61]
	v_mfma_f32_16x16x32_bf16 v[50:53], v[180:183], v[204:207], v[50:53]
	v_mfma_f32_16x16x32_bf16 v[42:45], v[172:175], v[212:215], v[42:45]
	v_mfma_f32_16x16x32_bf16 v[34:37], v[180:183], v[212:215], v[34:37]
	v_mfma_f32_16x16x32_bf16 v[26:29], v[172:175], v[220:223], v[26:29]
	v_mfma_f32_16x16x32_bf16 v[18:21], v[180:183], v[220:223], v[18:21]
	v_mfma_f32_16x16x32_bf16 v[10:13], v[172:175], v[228:231], v[10:13]
	v_mfma_f32_16x16x32_bf16 v[2:5], v[180:183], v[228:231], v[2:5]
	s_barrier
	s_setprio 0
	s_add_i32 s40, 0, 0x18000
	s_add_i32 s41, 0, 0x1c000
	v_add_u32_e32 v156, s40, v145
	v_add_u32_e32 v162, s41, v145
	ds_read_b128 v[140:143], v156
	ds_read_b128 v[148:151], v156 offset:1024
	ds_read_b128 v[152:155], v156 offset:2048
	ds_read_b128 v[156:159], v156 offset:3072
	ds_read_b128 v[164:167], v162
	ds_read_b128 v[172:175], v162 offset:1024
	ds_read_b128 v[176:179], v162 offset:2048
	ds_read_b128 v[180:183], v162 offset:3072
	s_add_u32 s18, s18, 0x80000
	s_addc_u32 s19, s19, 0
	s_mov_b32 m0, s25
	v_lshl_add_u64 v[236:237], s[18:19], 0, v[134:135]
	ds_read_b128 v[200:203], v147 offset:32768
	ds_read_b128 v[204:207], v147 offset:33792
	ds_read_b128 v[208:211], v147 offset:34816
	ds_read_b128 v[212:215], v147 offset:35840
	ds_read_b128 v[216:219], v147 offset:36864
	ds_read_b128 v[220:223], v147 offset:37888
	ds_read_b128 v[224:227], v147 offset:38912
	ds_read_b128 v[228:231], v147 offset:39936
	global_load_lds_dwordx4 v[236:237], off
	v_lshl_add_u64 v[236:237], s[18:19], 0, v[132:133]
	s_mov_b32 m0, s26
	s_nop 0
	global_load_lds_dwordx4 v[236:237], off
	s_waitcnt vmcnt(8)
	s_waitcnt lgkmcnt(0)
	s_setprio 1
	s_barrier
	v_mfma_f32_16x16x32_bf16 v[126:129], v[140:143], v[200:203], v[126:129]
	v_mfma_f32_16x16x32_bf16 v[118:121], v[152:155], v[200:203], v[118:121]
	v_mfma_f32_16x16x32_bf16 v[110:113], v[140:143], v[208:211], v[110:113]
	v_mfma_f32_16x16x32_bf16 v[102:105], v[152:155], v[208:211], v[102:105]
	v_mfma_f32_16x16x32_bf16 v[94:97], v[140:143], v[216:219], v[94:97]
	v_mfma_f32_16x16x32_bf16 v[86:89], v[152:155], v[216:219], v[86:89]
	v_mfma_f32_16x16x32_bf16 v[78:81], v[140:143], v[224:227], v[78:81]
	v_mfma_f32_16x16x32_bf16 v[70:73], v[152:155], v[224:227], v[70:73]
	v_mfma_f32_16x16x32_bf16 v[126:129], v[148:151], v[204:207], v[126:129]
	v_mfma_f32_16x16x32_bf16 v[118:121], v[156:159], v[204:207], v[118:121]
	v_mfma_f32_16x16x32_bf16 v[110:113], v[148:151], v[212:215], v[110:113]
	v_mfma_f32_16x16x32_bf16 v[102:105], v[156:159], v[212:215], v[102:105]
	v_mfma_f32_16x16x32_bf16 v[94:97], v[148:151], v[220:223], v[94:97]
	v_mfma_f32_16x16x32_bf16 v[86:89], v[156:159], v[220:223], v[86:89]
	v_mfma_f32_16x16x32_bf16 v[78:81], v[148:151], v[228:231], v[78:81]
	v_mfma_f32_16x16x32_bf16 v[70:73], v[156:159], v[228:231], v[70:73]
	v_mfma_f32_16x16x32_bf16 v[122:125], v[164:167], v[200:203], v[122:125]
	v_mfma_f32_16x16x32_bf16 v[114:117], v[176:179], v[200:203], v[114:117]
	v_mfma_f32_16x16x32_bf16 v[106:109], v[164:167], v[208:211], v[106:109]
	v_mfma_f32_16x16x32_bf16 v[98:101], v[176:179], v[208:211], v[98:101]
	v_mfma_f32_16x16x32_bf16 v[90:93], v[164:167], v[216:219], v[90:93]
	v_mfma_f32_16x16x32_bf16 v[82:85], v[176:179], v[216:219], v[82:85]
	v_mfma_f32_16x16x32_bf16 v[74:77], v[164:167], v[224:227], v[74:77]
	v_mfma_f32_16x16x32_bf16 v[66:69], v[176:179], v[224:227], v[66:69]
	v_mfma_f32_16x16x32_bf16 v[122:125], v[172:175], v[204:207], v[122:125]
	v_mfma_f32_16x16x32_bf16 v[114:117], v[180:183], v[204:207], v[114:117]
	v_mfma_f32_16x16x32_bf16 v[106:109], v[172:175], v[212:215], v[106:109]
	v_mfma_f32_16x16x32_bf16 v[98:101], v[180:183], v[212:215], v[98:101]
	v_mfma_f32_16x16x32_bf16 v[90:93], v[172:175], v[220:223], v[90:93]
	v_mfma_f32_16x16x32_bf16 v[82:85], v[180:183], v[220:223], v[82:85]
	v_mfma_f32_16x16x32_bf16 v[74:77], v[172:175], v[228:231], v[74:77]
	v_mfma_f32_16x16x32_bf16 v[66:69], v[180:183], v[228:231], v[66:69]
	s_barrier
; #define PG8_STAGE(bufoff, gbase, voff) do { _Pragma("unroll") for (int _i = 0; _i < 2; ++_i) \
;         __builtin_amdgcn_global_load_lds((const unsigned*)((const char*)(gbase) + (voff)[_i]), (PG8_LAS unsigned*)(lds + (bufoff) + ldsw + _i * 8192), 16, 0, 0); } while (0)
; #define PG8_LDA(dst, b, h) do { _Pragma("unroll") for (int m = 0; m < 4; ++m) _Pragma("unroll") for (int k = 0; k < 2; ++k) dst[m][k] = *(const PG8_LAS bf16x8*)(lds + PG8_SA(b, h) + aoff + m * 2048 + k * 1024); } while (0)
; #define PG8_MMA(ai, bj, At, Bt) do { __builtin_amdgcn_s_setprio(1); _Pragma("unroll") for (int m = 0; m < 4; ++m) _Pragma("unroll") for (int n = 0; n < 2; ++n) _Pragma("unroll") for (int k = 0; k < 2; ++k) \
;         acc[ai][bj][m][n] = __builtin_amdgcn_mfma_f32_16x16x32_bf16(Bt[n][k], At[m][k], acc[ai][bj][m][n], 0, 0, 0); __builtin_amdgcn_s_setprio(0); } while (0)
; #define PG8_WAIT_V(n) asm volatile("s_waitcnt vmcnt(" #n ")" ::: "memory")
; #define PG8_WAIT_L(n) asm volatile("s_waitcnt lgkmcnt(" #n ")" ::: "memory")
; #define PG8_BAR __builtin_amdgcn_s_barrier()
; #define PG8_SCHED __builtin_amdgcn_sched_barrier(0)
; template <class Epi, class Sched, bool ALIGN_EPI = false, bool SP2 = false>
; __device__ __forceinline__ void gemm_phase(PG8_LAS unsigned char* lds, const Gemm g, const Sched& S, const Epi& E) {
;     ...
;             PG8_LDA(At, 1, 1); PG8_STAGE(PG8_SB(1, 0), b3, voffB); PG8_STAGE(PG8_SB(1, 1), b3 + hstep, voffB); PG8_STAGE(PG8_SA(1, 0), a3, voffA);
;             PG8_WAIT_V(8); PG8_WAIT_L(0); PG8_BAR; PG8_MMA(1, 0, At, B0); PG8_MMA(1, 1, At, B1); PG8_BAR; PG8_SCHED;
;     ...
;         if constexpr (ALIGN_EPI) { if (wr == 0) PG8_BAR; }
	s_setprio 0
	s_add_i32 s18, s40, s22
	v_lshl_add_u64 v[160:161], v[160:161], 0, s[44:45]
	s_mov_b32 m0, s18
	ds_read_b128 v[200:203], v147 offset:49152
	ds_read_b128 v[204:207], v147 offset:50176
	ds_read_b128 v[208:211], v147 offset:51200
	ds_read_b128 v[212:215], v147 offset:52224
	ds_read_b128 v[216:219], v147 offset:53248
	ds_read_b128 v[220:223], v147 offset:54272
	ds_read_b128 v[224:227], v147 offset:55296
	ds_read_b128 v[228:231], v147 offset:56320
	global_load_lds_dwordx4 v[160:161], off
	s_add_i32 m0, s18, 0x2000
	s_add_u32 s16, s16, 0x80080
	v_lshl_add_u64 v[160:161], v[184:185], 0, s[44:45]
	s_addc_u32 s17, s17, 0
	s_add_i32 s18, s41, s22
	global_load_lds_dwordx4 v[160:161], off
	v_lshl_add_u64 v[160:161], s[16:17], 0, v[0:1]
	s_mov_b32 m0, s18
	s_nop 0
	global_load_lds_dwordx4 v[160:161], off
	v_lshl_add_u64 v[160:161], s[16:17], 0, v[130:131]
	s_add_i32 m0, s18, 0x2000
	s_nop 0
	global_load_lds_dwordx4 v[160:161], off
	v_lshl_add_u64 v[160:161], v[232:233], 0, s[44:45]
	s_mov_b32 m0, s27
	s_nop 0
	global_load_lds_dwordx4 v[160:161], off
	v_lshl_add_u64 v[160:161], v[234:235], 0, s[44:45]
	s_mov_b32 m0, s28
	s_nop 0
	global_load_lds_dwordx4 v[160:161], off
	s_waitcnt vmcnt(8)
	s_waitcnt lgkmcnt(0)
	s_setprio 1
	s_barrier
	v_mfma_f32_16x16x32_bf16 v[62:65], v[140:143], v[200:203], v[62:65]
	v_mfma_f32_16x16x32_bf16 v[54:57], v[152:155], v[200:203], v[54:57]
	v_mfma_f32_16x16x32_bf16 v[46:49], v[140:143], v[208:211], v[46:49]
	v_mfma_f32_16x16x32_bf16 v[38:41], v[152:155], v[208:211], v[38:41]
	v_mfma_f32_16x16x32_bf16 v[30:33], v[140:143], v[216:219], v[30:33]
	v_mfma_f32_16x16x32_bf16 v[22:25], v[152:155], v[216:219], v[22:25]
	v_mfma_f32_16x16x32_bf16 v[14:17], v[140:143], v[224:227], v[14:17]
	v_mfma_f32_16x16x32_bf16 v[6:9], v[152:155], v[224:227], v[6:9]
	v_mfma_f32_16x16x32_bf16 v[62:65], v[148:151], v[204:207], v[62:65]
	v_mfma_f32_16x16x32_bf16 v[54:57], v[156:159], v[204:207], v[54:57]
	v_mfma_f32_16x16x32_bf16 v[46:49], v[148:151], v[212:215], v[46:49]
	v_mfma_f32_16x16x32_bf16 v[38:41], v[156:159], v[212:215], v[38:41]
	v_mfma_f32_16x16x32_bf16 v[30:33], v[148:151], v[220:223], v[30:33]
	v_mfma_f32_16x16x32_bf16 v[22:25], v[156:159], v[220:223], v[22:25]
	v_mfma_f32_16x16x32_bf16 v[14:17], v[148:151], v[228:231], v[14:17]
	v_mfma_f32_16x16x32_bf16 v[6:9], v[156:159], v[228:231], v[6:9]
	v_mfma_f32_16x16x32_bf16 v[58:61], v[164:167], v[200:203], v[58:61]
	v_mfma_f32_16x16x32_bf16 v[50:53], v[176:179], v[200:203], v[50:53]
	v_mfma_f32_16x16x32_bf16 v[42:45], v[164:167], v[208:211], v[42:45]
	v_mfma_f32_16x16x32_bf16 v[34:37], v[176:179], v[208:211], v[34:37]
	v_mfma_f32_16x16x32_bf16 v[26:29], v[164:167], v[216:219], v[26:29]
	v_mfma_f32_16x16x32_bf16 v[18:21], v[176:179], v[216:219], v[18:21]
	v_mfma_f32_16x16x32_bf16 v[10:13], v[164:167], v[224:227], v[10:13]
	v_mfma_f32_16x16x32_bf16 v[2:5], v[176:179], v[224:227], v[2:5]
	v_mfma_f32_16x16x32_bf16 v[58:61], v[172:175], v[204:207], v[58:61]
	v_mfma_f32_16x16x32_bf16 v[50:53], v[180:183], v[204:207], v[50:53]
	v_mfma_f32_16x16x32_bf16 v[42:45], v[172:175], v[212:215], v[42:45]
	v_mfma_f32_16x16x32_bf16 v[34:37], v[180:183], v[212:215], v[34:37]
	v_mfma_f32_16x16x32_bf16 v[26:29], v[172:175], v[220:223], v[26:29]
	v_mfma_f32_16x16x32_bf16 v[18:21], v[180:183], v[220:223], v[18:21]
	v_mfma_f32_16x16x32_bf16 v[10:13], v[172:175], v[228:231], v[10:13]
	v_mfma_f32_16x16x32_bf16 v[2:5], v[180:183], v[228:231], v[2:5]
	s_barrier
	s_setprio 0
	s_add_i32 s37, s37, 2
	s_add_u32 s14, s14, 0x100
	s_addc_u32 s15, s15, 0
	s_add_u32 s35, s35, 0x100
	s_addc_u32 s36, s36, 0
	s_cmp_gt_u32 s37, 29
	s_cbranch_scc0 .LBB0_966
	s_and_b64 vcc, exec, s[4:5]
	s_cbranch_vccz .LBB0_969
	s_barrier

; #define PG8_STAGE(bufoff, gbase, voff) do { _Pragma("unroll") for (int _i = 0; _i < 2; ++_i) \
;         __builtin_amdgcn_global_load_lds((const unsigned*)((const char*)(gbase) + (voff)[_i]), (PG8_LAS unsigned*)(lds + (bufoff) + ldsw + _i * 8192), 16, 0, 0); } while (0)
; #define PG8_LDA(dst, b, h) do { _Pragma("unroll") for (int m = 0; m < 4; ++m) _Pragma("unroll") for (int k = 0; k < 2; ++k) dst[m][k] = *(const PG8_LAS bf16x8*)(lds + PG8_SA(b, h) + aoff + m * 2048 + k * 1024); } while (0)
; #define PG8_LDB(dst, b, h) do { _Pragma("unroll") for (int n = 0; n < 2; ++n) _Pragma("unroll") for (int k = 0; k < 2; ++k) dst[n][k] = *(const PG8_LAS bf16x8*)(lds + PG8_SB(b, h) + boff + n * 2048 + k * 1024); } while (0)
; #define PG8_MMA(ai, bj, At, Bt) do { __builtin_amdgcn_s_setprio(1); _Pragma("unroll") for (int m = 0; m < 4; ++m) _Pragma("unroll") for (int n = 0; n < 2; ++n) _Pragma("unroll") for (int k = 0; k < 2; ++k) \
;         acc[ai][bj][m][n] = __builtin_amdgcn_mfma_f32_16x16x32_bf16(Bt[n][k], At[m][k], acc[ai][bj][m][n], 0, 0, 0); __builtin_amdgcn_s_setprio(0); } while (0)
; #define PG8_WAIT_V(n) asm volatile("s_waitcnt vmcnt(" #n ")" ::: "memory")
; #define PG8_WAIT_L(n) asm volatile("s_waitcnt lgkmcnt(" #n ")" ::: "memory")
; template <class Epi, class Sched, bool ALIGN_EPI = false, bool SP2 = false>
; __device__ __forceinline__ void gemm_phase(PG8_LAS unsigned char* lds, const Gemm g, const Sched& S, const Epi& E) {
;     ...
;             const bool last = (t == nt - 2);
;             const char* a1 = cA + (size_t)(t + 1) * kstep;
;             const char* a2 = last ? nA : cA + (size_t)(t + 2) * kstep; const char* b2 = last ? nB : cB + (size_t)(t + 2) * kstep;
;             const char* a3 = a2 + kstep; const char* b3 = b2 + kstep;
;             if (last && has_next) S.a_ready(nxt);
;             if constexpr (SP2) {
;             PG8_LDB(B0, 0, 0); PG8_LDB(B1, 0, 1); PG8_SCHED; PG8_LDA(At, 0, 0); PG8_STAGE(PG8_SA(1, 1), a1 + hstep, voffA);
;             PG8_WAIT_V(8); PG8_WAIT_L(0); PG8_BAR; PG8_MMA(0, 0, At, B0); PG8_MMA(0, 1, At, B1); PG8_BAR; PG8_SCHED;
;             PG8_LDA(At, 0, 1); PG8_STAGE(PG8_SB(0, 0), b2, voffB); PG8_STAGE(PG8_SB(0, 1), b2 + hstep, voffB); PG8_STAGE(PG8_SA(0, 0), a2, voffA);
;             PG8_WAIT_V(8); PG8_WAIT_L(0); PG8_BAR; PG8_MMA(1, 0, At, B0); PG8_MMA(1, 1, At, B1); PG8_BAR; PG8_SCHED;
.LBB0_1066:
	s_add_u32 s12, s6, s10
	s_addc_u32 s13, s7, s11
	s_add_u32 s12, s12, 0x100
	s_addc_u32 s13, s13, 0
	s_add_u32 s40, s37, s10
	s_addc_u32 s41, s38, s11
	s_add_i32 s42, 0, 0x10000
	s_cmpk_eq_i32 s10, 0x2b00
	s_cselect_b32 s15, s9, s13
	s_cselect_b32 s14, s8, s12
	v_add_u32_e32 v160, s42, v144
	s_cselect_b32 s13, s5, s41
	s_cselect_b32 s12, s4, s40
	s_add_i32 s43, 0, 0x14000
	ds_read_b128 v[146:149], v160
	ds_read_b128 v[150:153], v160 offset:1024
	ds_read_b128 v[156:159], v160 offset:2048
	ds_read_b128 v[164:167], v160 offset:3072
	v_add_u32_e32 v160, s43, v144
	ds_read_b128 v[172:175], v160
	ds_read_b128 v[180:183], v160 offset:1024
	ds_read_b128 v[200:203], v160 offset:2048
	ds_read_b128 v[204:207], v160 offset:3072
	v_lshl_add_u64 v[160:161], v[140:141], 0, s[10:11]
	s_add_i32 m0, s26, 0xc000
	ds_read_b128 v[208:211], v145
	ds_read_b128 v[212:215], v145 offset:1024
	ds_read_b128 v[216:219], v145 offset:2048
	ds_read_b128 v[220:223], v145 offset:3072
	ds_read_b128 v[224:227], v145 offset:4096
	ds_read_b128 v[228:231], v145 offset:5120
	ds_read_b128 v[232:235], v145 offset:6144
	ds_read_b128 v[236:239], v145 offset:7168
	global_load_lds_dwordx4 v[160:161], off
	v_lshl_add_u64 v[160:161], v[142:143], 0, s[10:11]
	s_add_i32 m0, s26, 0xe000
	s_nop 0
	global_load_lds_dwordx4 v[160:161], off
	s_waitcnt vmcnt(8)
	s_waitcnt lgkmcnt(0)
	s_setprio 1
	s_barrier
	v_mfma_f32_16x16x32_bf16 v[126:129], v[146:149], v[208:211], v[126:129]
	v_mfma_f32_16x16x32_bf16 v[122:125], v[156:159], v[208:211], v[122:125]
	v_mfma_f32_16x16x32_bf16 v[110:113], v[146:149], v[216:219], v[110:113]
	v_mfma_f32_16x16x32_bf16 v[106:109], v[156:159], v[216:219], v[106:109]
	v_mfma_f32_16x16x32_bf16 v[94:97], v[146:149], v[224:227], v[94:97]
	v_mfma_f32_16x16x32_bf16 v[90:93], v[156:159], v[224:227], v[90:93]
	v_mfma_f32_16x16x32_bf16 v[78:81], v[146:149], v[232:235], v[78:81]
	v_mfma_f32_16x16x32_bf16 v[74:77], v[156:159], v[232:235], v[74:77]
	v_mfma_f32_16x16x32_bf16 v[126:129], v[150:153], v[212:215], v[126:129]
	v_mfma_f32_16x16x32_bf16 v[122:125], v[164:167], v[212:215], v[122:125]
	v_mfma_f32_16x16x32_bf16 v[110:113], v[150:153], v[220:223], v[110:113]
	v_mfma_f32_16x16x32_bf16 v[106:109], v[164:167], v[220:223], v[106:109]
	v_mfma_f32_16x16x32_bf16 v[94:97], v[150:153], v[228:231], v[94:97]
	v_mfma_f32_16x16x32_bf16 v[90:93], v[164:167], v[228:231], v[90:93]
	v_mfma_f32_16x16x32_bf16 v[78:81], v[150:153], v[236:239], v[78:81]
	v_mfma_f32_16x16x32_bf16 v[74:77], v[164:167], v[236:239], v[74:77]
	v_mfma_f32_16x16x32_bf16 v[118:121], v[172:175], v[208:211], v[118:121]
	v_mfma_f32_16x16x32_bf16 v[114:117], v[200:203], v[208:211], v[114:117]
	v_mfma_f32_16x16x32_bf16 v[102:105], v[172:175], v[216:219], v[102:105]
	v_mfma_f32_16x16x32_bf16 v[98:101], v[200:203], v[216:219], v[98:101]
	v_mfma_f32_16x16x32_bf16 v[86:89], v[172:175], v[224:227], v[86:89]
	v_mfma_f32_16x16x32_bf16 v[82:85], v[200:203], v[224:227], v[82:85]
	v_mfma_f32_16x16x32_bf16 v[70:73], v[172:175], v[232:235], v[70:73]
	v_mfma_f32_16x16x32_bf16 v[66:69], v[200:203], v[232:235], v[66:69]
	v_mfma_f32_16x16x32_bf16 v[118:121], v[180:183], v[212:215], v[118:121]
	v_mfma_f32_16x16x32_bf16 v[114:117], v[204:207], v[212:215], v[114:117]
	v_mfma_f32_16x16x32_bf16 v[102:105], v[180:183], v[220:223], v[102:105]
	v_mfma_f32_16x16x32_bf16 v[98:101], v[204:207], v[220:223], v[98:101]
	v_mfma_f32_16x16x32_bf16 v[86:89], v[180:183], v[228:231], v[86:89]
	v_mfma_f32_16x16x32_bf16 v[82:85], v[204:207], v[228:231], v[82:85]
	v_mfma_f32_16x16x32_bf16 v[70:73], v[180:183], v[236:239], v[70:73]
	v_mfma_f32_16x16x32_bf16 v[66:69], v[204:207], v[236:239], v[66:69]
	s_barrier
	s_setprio 0
	s_add_i32 s40, s42, s25
	v_lshl_add_u64 v[160:161], s[12:13], 0, v[0:1]
	s_mov_b32 m0, s40
	ds_read_b128 v[208:211], v145 offset:16384
	ds_read_b128 v[212:215], v145 offset:17408
	ds_read_b128 v[216:219], v145 offset:18432
	ds_read_b128 v[220:223], v145 offset:19456
	ds_read_b128 v[224:227], v145 offset:20480
	ds_read_b128 v[228:231], v145 offset:21504
	ds_read_b128 v[232:235], v145 offset:22528
	ds_read_b128 v[236:239], v145 offset:23552
	global_load_lds_dwordx4 v[160:161], off
	s_add_i32 m0, s40, 0x2000
	s_add_u32 s40, s12, 0x160000
	v_lshl_add_u64 v[176:177], s[12:13], 0, v[130:131]
	s_addc_u32 s41, s13, 0
	s_add_i32 s42, s43, s25
	global_load_lds_dwordx4 v[176:177], off
	v_lshl_add_u64 v[184:185], s[40:41], 0, v[0:1]
	s_mov_b32 m0, s42
	v_lshl_add_u64 v[240:241], s[14:15], 0, v[132:133]
	global_load_lds_dwordx4 v[184:185], off
	v_lshl_add_u64 v[184:185], s[40:41], 0, v[130:131]
	s_add_i32 m0, s42, 0x2000
	s_nop 0
	global_load_lds_dwordx4 v[184:185], off
	v_lshl_add_u64 v[184:185], s[14:15], 0, v[134:135]
	s_mov_b32 m0, s26
	s_nop 0
	global_load_lds_dwordx4 v[184:185], off
	s_mov_b32 m0, s27
	s_nop 0
	global_load_lds_dwordx4 v[240:241], off
	s_waitcnt vmcnt(8)
	s_waitcnt lgkmcnt(0)
	s_setprio 1
	s_barrier
; #define PG8_STAGE(bufoff, gbase, voff) do { _Pragma("unroll") for (int _i = 0; _i < 2; ++_i) \
;         __builtin_amdgcn_global_load_lds((const unsigned*)((const char*)(gbase) + (voff)[_i]), (PG8_LAS unsigned*)(lds + (bufoff) + ldsw + _i * 8192), 16, 0, 0); } while (0)
; #define PG8_LDA(dst, b, h) do { _Pragma("unroll") for (int m = 0; m < 4; ++m) _Pragma("unroll") for (int k = 0; k < 2; ++k) dst[m][k] = *(const PG8_LAS bf16x8*)(lds + PG8_SA(b, h) + aoff + m * 2048 + k * 1024); } while (0)
; #define PG8_LDB(dst, b, h) do { _Pragma("unroll") for (int n = 0; n < 2; ++n) _Pragma("unroll") for (int k = 0; k < 2; ++k) dst[n][k] = *(const PG8_LAS bf16x8*)(lds + PG8_SB(b, h) + boff + n * 2048 + k * 1024); } while (0)
; #define PG8_MMA(ai, bj, At, Bt) do { __builtin_amdgcn_s_setprio(1); _Pragma("unroll") for (int m = 0; m < 4; ++m) _Pragma("unroll") for (int n = 0; n < 2; ++n) _Pragma("unroll") for (int k = 0; k < 2; ++k) \
;         acc[ai][bj][m][n] = __builtin_amdgcn_mfma_f32_16x16x32_bf16(Bt[n][k], At[m][k], acc[ai][bj][m][n], 0, 0, 0); __builtin_amdgcn_s_setprio(0); } while (0)
; #define PG8_WAIT_V(n) asm volatile("s_waitcnt vmcnt(" #n ")" ::: "memory")
; #define PG8_WAIT_L(n) asm volatile("s_waitcnt lgkmcnt(" #n ")" ::: "memory")
; #define PG8_BAR __builtin_amdgcn_s_barrier()
; #define PG8_SCHED __builtin_amdgcn_sched_barrier(0)
; template <class Epi, class Sched, bool ALIGN_EPI = false, bool SP2 = false>
; __device__ __forceinline__ void gemm_phase(PG8_LAS unsigned char* lds, const Gemm g, const Sched& S, const Epi& E) {
;     ...
;             PG8_WAIT_V(8); PG8_WAIT_L(0); PG8_BAR; PG8_MMA(1, 0, At, B0); PG8_MMA(1, 1, At, B1); PG8_BAR; PG8_SCHED;
;             PG8_LDB(B0, 1, 0); PG8_LDB(B1, 1, 1); PG8_SCHED; PG8_LDA(At, 1, 0); PG8_STAGE(PG8_SA(0, 1), a2 + hstep, voffA);
;             PG8_WAIT_V(8); PG8_WAIT_L(0); PG8_BAR; PG8_MMA(0, 0, At, B0); PG8_MMA(0, 1, At, B1); PG8_BAR; PG8_SCHED;
	v_mfma_f32_16x16x32_bf16 v[62:65], v[146:149], v[208:211], v[62:65]
	v_mfma_f32_16x16x32_bf16 v[58:61], v[156:159], v[208:211], v[58:61]
	v_mfma_f32_16x16x32_bf16 v[46:49], v[146:149], v[216:219], v[46:49]
	v_mfma_f32_16x16x32_bf16 v[42:45], v[156:159], v[216:219], v[42:45]
	v_mfma_f32_16x16x32_bf16 v[30:33], v[146:149], v[224:227], v[30:33]
	v_mfma_f32_16x16x32_bf16 v[26:29], v[156:159], v[224:227], v[26:29]
	v_mfma_f32_16x16x32_bf16 v[14:17], v[146:149], v[232:235], v[14:17]
	v_mfma_f32_16x16x32_bf16 v[10:13], v[156:159], v[232:235], v[10:13]
	v_mfma_f32_16x16x32_bf16 v[62:65], v[150:153], v[212:215], v[62:65]
	v_mfma_f32_16x16x32_bf16 v[58:61], v[164:167], v[212:215], v[58:61]
	v_mfma_f32_16x16x32_bf16 v[46:49], v[150:153], v[220:223], v[46:49]
	v_mfma_f32_16x16x32_bf16 v[42:45], v[164:167], v[220:223], v[42:45]
	v_mfma_f32_16x16x32_bf16 v[30:33], v[150:153], v[228:231], v[30:33]
	v_mfma_f32_16x16x32_bf16 v[26:29], v[164:167], v[228:231], v[26:29]
	v_mfma_f32_16x16x32_bf16 v[14:17], v[150:153], v[236:239], v[14:17]
	v_mfma_f32_16x16x32_bf16 v[10:13], v[164:167], v[236:239], v[10:13]
	v_mfma_f32_16x16x32_bf16 v[54:57], v[172:175], v[208:211], v[54:57]
	v_mfma_f32_16x16x32_bf16 v[50:53], v[200:203], v[208:211], v[50:53]
	v_mfma_f32_16x16x32_bf16 v[38:41], v[172:175], v[216:219], v[38:41]
	v_mfma_f32_16x16x32_bf16 v[34:37], v[200:203], v[216:219], v[34:37]
	v_mfma_f32_16x16x32_bf16 v[22:25], v[172:175], v[224:227], v[22:25]
	v_mfma_f32_16x16x32_bf16 v[18:21], v[200:203], v[224:227], v[18:21]
	v_mfma_f32_16x16x32_bf16 v[6:9], v[172:175], v[232:235], v[6:9]
	v_mfma_f32_16x16x32_bf16 v[2:5], v[200:203], v[232:235], v[2:5]
	v_mfma_f32_16x16x32_bf16 v[54:57], v[180:183], v[212:215], v[54:57]
	v_mfma_f32_16x16x32_bf16 v[50:53], v[204:207], v[212:215], v[50:53]
	v_mfma_f32_16x16x32_bf16 v[38:41], v[180:183], v[220:223], v[38:41]
	v_mfma_f32_16x16x32_bf16 v[34:37], v[204:207], v[220:223], v[34:37]
	v_mfma_f32_16x16x32_bf16 v[22:25], v[180:183], v[228:231], v[22:25]
	v_mfma_f32_16x16x32_bf16 v[18:21], v[204:207], v[228:231], v[18:21]
	v_mfma_f32_16x16x32_bf16 v[6:9], v[180:183], v[236:239], v[6:9]
	v_mfma_f32_16x16x32_bf16 v[2:5], v[204:207], v[236:239], v[2:5]
	s_barrier
	s_setprio 0
	s_add_i32 s40, 0, 0x18000
	v_add_u32_e32 v162, s40, v144
	s_add_i32 s41, 0, 0x1c000
	ds_read_b128 v[146:149], v162
	ds_read_b128 v[150:153], v162 offset:1024
	ds_read_b128 v[156:159], v162 offset:2048
	ds_read_b128 v[164:167], v162 offset:3072
	v_add_u32_e32 v162, s41, v144
	ds_read_b128 v[172:175], v162
	ds_read_b128 v[180:183], v162 offset:1024
	ds_read_b128 v[200:203], v162 offset:2048
	ds_read_b128 v[204:207], v162 offset:3072
	s_add_u32 s14, s14, 0x160000
	s_addc_u32 s15, s15, 0
	s_mov_b32 m0, s28
	v_lshl_add_u64 v[242:243], s[14:15], 0, v[134:135]
	ds_read_b128 v[208:211], v145 offset:32768
	ds_read_b128 v[212:215], v145 offset:33792
	ds_read_b128 v[216:219], v145 offset:34816
	ds_read_b128 v[220:223], v145 offset:35840
	ds_read_b128 v[224:227], v145 offset:36864
	ds_read_b128 v[228:231], v145 offset:37888
	ds_read_b128 v[232:235], v145 offset:38912
	ds_read_b128 v[236:239], v145 offset:39936
	global_load_lds_dwordx4 v[242:243], off
	v_lshl_add_u64 v[242:243], s[14:15], 0, v[132:133]
	s_mov_b32 m0, s29
	s_nop 0
	global_load_lds_dwordx4 v[242:243], off
	s_waitcnt vmcnt(8)
	s_waitcnt lgkmcnt(0)
	s_setprio 1
	s_barrier
	v_mfma_f32_16x16x32_bf16 v[126:129], v[146:149], v[208:211], v[126:129]
	v_mfma_f32_16x16x32_bf16 v[122:125], v[156:159], v[208:211], v[122:125]
	v_mfma_f32_16x16x32_bf16 v[110:113], v[146:149], v[216:219], v[110:113]
	v_mfma_f32_16x16x32_bf16 v[106:109], v[156:159], v[216:219], v[106:109]
	v_mfma_f32_16x16x32_bf16 v[94:97], v[146:149], v[224:227], v[94:97]
	v_mfma_f32_16x16x32_bf16 v[90:93], v[156:159], v[224:227], v[90:93]
	v_mfma_f32_16x16x32_bf16 v[78:81], v[146:149], v[232:235], v[78:81]
	v_mfma_f32_16x16x32_bf16 v[74:77], v[156:159], v[232:235], v[74:77]
	v_mfma_f32_16x16x32_bf16 v[126:129], v[150:153], v[212:215], v[126:129]
	v_mfma_f32_16x16x32_bf16 v[122:125], v[164:167], v[212:215], v[122:125]
	v_mfma_f32_16x16x32_bf16 v[110:113], v[150:153], v[220:223], v[110:113]
	v_mfma_f32_16x16x32_bf16 v[106:109], v[164:167], v[220:223], v[106:109]
	v_mfma_f32_16x16x32_bf16 v[94:97], v[150:153], v[228:231], v[94:97]
	v_mfma_f32_16x16x32_bf16 v[90:93], v[164:167], v[228:231], v[90:93]
	v_mfma_f32_16x16x32_bf16 v[78:81], v[150:153], v[236:239], v[78:81]
	v_mfma_f32_16x16x32_bf16 v[74:77], v[164:167], v[236:239], v[74:77]
	v_mfma_f32_16x16x32_bf16 v[118:121], v[172:175], v[208:211], v[118:121]
	v_mfma_f32_16x16x32_bf16 v[114:117], v[200:203], v[208:211], v[114:117]
	v_mfma_f32_16x16x32_bf16 v[102:105], v[172:175], v[216:219], v[102:105]
	v_mfma_f32_16x16x32_bf16 v[98:101], v[200:203], v[216:219], v[98:101]
	v_mfma_f32_16x16x32_bf16 v[86:89], v[172:175], v[224:227], v[86:89]
	v_mfma_f32_16x16x32_bf16 v[82:85], v[200:203], v[224:227], v[82:85]
	v_mfma_f32_16x16x32_bf16 v[70:73], v[172:175], v[232:235], v[70:73]
	v_mfma_f32_16x16x32_bf16 v[66:69], v[200:203], v[232:235], v[66:69]
	v_mfma_f32_16x16x32_bf16 v[118:121], v[180:183], v[212:215], v[118:121]
	v_mfma_f32_16x16x32_bf16 v[114:117], v[204:207], v[212:215], v[114:117]
	v_mfma_f32_16x16x32_bf16 v[102:105], v[180:183], v[220:223], v[102:105]
	v_mfma_f32_16x16x32_bf16 v[98:101], v[204:207], v[220:223], v[98:101]
	v_mfma_f32_16x16x32_bf16 v[86:89], v[180:183], v[228:231], v[86:89]
	v_mfma_f32_16x16x32_bf16 v[82:85], v[204:207], v[228:231], v[82:85]
	v_mfma_f32_16x16x32_bf16 v[70:73], v[180:183], v[236:239], v[70:73]
	v_mfma_f32_16x16x32_bf16 v[66:69], v[204:207], v[236:239], v[66:69]
	s_barrier
; #define PG8_WAIT_V(n) asm volatile("s_waitcnt vmcnt(" #n ")" ::: "memory")
; #define PG8_BAR __builtin_amdgcn_s_barrier()
; template <class Epi, class Sched, bool ALIGN_EPI = false, bool SP2 = false>
; __device__ __forceinline__ void gemm_phase(PG8_LAS unsigned char* lds, const Gemm g, const Sched& S, const Epi& E) {
;     ...
;             PG8_LDA(At, 1, 1); PG8_STAGE(PG8_SB(1, 0), b3, voffB); PG8_STAGE(PG8_SB(1, 1), b3 + hstep, voffB); PG8_STAGE(PG8_SA(1, 0), a3, voffA);
;             PG8_WAIT_V(8); PG8_WAIT_L(0); PG8_BAR; PG8_MMA(1, 0, At, B0); PG8_MMA(1, 1, At, B1); PG8_BAR; PG8_SCHED;
;             } else {
;             PG8_LDB(B0, 0, 0); PG8_SCHED; PG8_LDA(At, 0, 0); PG8_STAGE(PG8_SA(1, 1), a1 + hstep, voffA);
;             PG8_WAIT_L(8); PG8_BAR; PG8_WAIT_L(0); PG8_MMA(0, 0, At, B0); PG8_BAR; PG8_SCHED;
;             PG8_LDB(B1, 0, 1); PG8_STAGE(PG8_SB(0, 0), b2, voffB);
;             PG8_BAR; PG8_WAIT_L(0); PG8_MMA(0, 1, At, B1); PG8_BAR;
;             PG8_LDA(At, 0, 1); PG8_STAGE(PG8_SA(0, 0), a2, voffA);
;             PG8_BAR; PG8_WAIT_L(0); PG8_MMA(1, 0, At, B0); PG8_BAR; PG8_SCHED;
;             PG8_STAGE(PG8_SB(0, 1), b2 + hstep, voffB);
;             PG8_WAIT_V(6); PG8_BAR; PG8_MMA(1, 1, At, B1); PG8_BAR;
;             PG8_LDB(B0, 1, 0); PG8_SCHED; PG8_LDA(At, 1, 0); PG8_STAGE(PG8_SA(0, 1), a2 + hstep, voffA);
;             PG8_WAIT_L(8); PG8_BAR; PG8_WAIT_L(0); PG8_MMA(0, 0, At, B0); PG8_BAR; PG8_SCHED;
;             PG8_LDB(B1, 1, 1); PG8_STAGE(PG8_SB(1, 0), b3, voffB);
;             PG8_BAR; PG8_WAIT_L(0); PG8_MMA(0, 1, At, B1); PG8_BAR;
;             PG8_LDA(At, 1, 1); PG8_STAGE(PG8_SA(1, 0), a3, voffA);
;             PG8_BAR; PG8_WAIT_L(0); PG8_MMA(1, 0, At, B0); PG8_BAR; PG8_SCHED;
;             PG8_STAGE(PG8_SB(1, 1), b3 + hstep, voffB);
;             PG8_WAIT_V(6); PG8_BAR; PG8_MMA(1, 1, At, B1); PG8_BAR;
;             }
;         }
;         if constexpr (ALIGN_EPI) { if (wr == 0) PG8_BAR; }
;         if constexpr (!Epi::AFTER_DRAIN) { E(acc, cur, wr, wc, fr, fq); S.done(cur); }
;         if (!has_next) break;
; #pragma unroll
;         for (int a = 0; a < 2; ++a)
; #pragma unroll
;             for (int b = 0; b < 2; ++b)
; #pragma unroll
;                 for (int m = 0; m < 4; ++m)
; #pragma unroll
;                     for (int n = 0; n < 2; ++n) acc[a][b][m][n] = (f32x4){0.f, 0.f, 0.f, 0.f};
;         cur = nxt; cA = nA; cB = nB; ++ui;
	s_setprio 0
	s_add_i32 s14, s40, s25
	v_lshl_add_u64 v[160:161], v[160:161], 0, s[44:45]
	s_mov_b32 m0, s14
	ds_read_b128 v[208:211], v145 offset:49152
	ds_read_b128 v[212:215], v145 offset:50176
	ds_read_b128 v[216:219], v145 offset:51200
	ds_read_b128 v[220:223], v145 offset:52224
	ds_read_b128 v[224:227], v145 offset:53248
	ds_read_b128 v[228:231], v145 offset:54272
	ds_read_b128 v[232:235], v145 offset:55296
	ds_read_b128 v[236:239], v145 offset:56320
	global_load_lds_dwordx4 v[160:161], off
	s_add_i32 m0, s14, 0x2000
	s_add_u32 s12, s12, 0x160080
	v_lshl_add_u64 v[160:161], v[176:177], 0, s[44:45]
	s_addc_u32 s13, s13, 0
	s_add_i32 s14, s41, s25
	global_load_lds_dwordx4 v[160:161], off
	v_lshl_add_u64 v[160:161], s[12:13], 0, v[0:1]
	s_mov_b32 m0, s14
	s_nop 0
	global_load_lds_dwordx4 v[160:161], off
	v_lshl_add_u64 v[160:161], s[12:13], 0, v[130:131]
	s_add_i32 m0, s14, 0x2000
	s_nop 0
	global_load_lds_dwordx4 v[160:161], off
	v_lshl_add_u64 v[160:161], v[184:185], 0, s[44:45]
	s_mov_b32 m0, s30
	s_nop 0
	global_load_lds_dwordx4 v[160:161], off
	v_lshl_add_u64 v[160:161], v[240:241], 0, s[44:45]
	s_mov_b32 m0, s31
	s_nop 0
	global_load_lds_dwordx4 v[160:161], off
	s_waitcnt vmcnt(8)
	s_waitcnt lgkmcnt(0)
	s_setprio 1
	s_barrier
	v_mfma_f32_16x16x32_bf16 v[62:65], v[146:149], v[208:211], v[62:65]
	v_mfma_f32_16x16x32_bf16 v[58:61], v[156:159], v[208:211], v[58:61]
	v_mfma_f32_16x16x32_bf16 v[46:49], v[146:149], v[216:219], v[46:49]
	v_mfma_f32_16x16x32_bf16 v[42:45], v[156:159], v[216:219], v[42:45]
	v_mfma_f32_16x16x32_bf16 v[30:33], v[146:149], v[224:227], v[30:33]
	v_mfma_f32_16x16x32_bf16 v[26:29], v[156:159], v[224:227], v[26:29]
	v_mfma_f32_16x16x32_bf16 v[14:17], v[146:149], v[232:235], v[14:17]
	v_mfma_f32_16x16x32_bf16 v[10:13], v[156:159], v[232:235], v[10:13]
	v_mfma_f32_16x16x32_bf16 v[62:65], v[150:153], v[212:215], v[62:65]
	v_mfma_f32_16x16x32_bf16 v[58:61], v[164:167], v[212:215], v[58:61]
	v_mfma_f32_16x16x32_bf16 v[46:49], v[150:153], v[220:223], v[46:49]
	v_mfma_f32_16x16x32_bf16 v[42:45], v[164:167], v[220:223], v[42:45]
	v_mfma_f32_16x16x32_bf16 v[30:33], v[150:153], v[228:231], v[30:33]
	v_mfma_f32_16x16x32_bf16 v[26:29], v[164:167], v[228:231], v[26:29]
	v_mfma_f32_16x16x32_bf16 v[14:17], v[150:153], v[236:239], v[14:17]
	v_mfma_f32_16x16x32_bf16 v[10:13], v[164:167], v[236:239], v[10:13]
	v_mfma_f32_16x16x32_bf16 v[54:57], v[172:175], v[208:211], v[54:57]
	v_mfma_f32_16x16x32_bf16 v[50:53], v[200:203], v[208:211], v[50:53]
	v_mfma_f32_16x16x32_bf16 v[38:41], v[172:175], v[216:219], v[38:41]
	v_mfma_f32_16x16x32_bf16 v[34:37], v[200:203], v[216:219], v[34:37]
	v_mfma_f32_16x16x32_bf16 v[22:25], v[172:175], v[224:227], v[22:25]
	v_mfma_f32_16x16x32_bf16 v[18:21], v[200:203], v[224:227], v[18:21]
	v_mfma_f32_16x16x32_bf16 v[6:9], v[172:175], v[232:235], v[6:9]
	v_mfma_f32_16x16x32_bf16 v[2:5], v[200:203], v[232:235], v[2:5]
	v_mfma_f32_16x16x32_bf16 v[54:57], v[180:183], v[212:215], v[54:57]
	v_mfma_f32_16x16x32_bf16 v[50:53], v[204:207], v[212:215], v[50:53]
	v_mfma_f32_16x16x32_bf16 v[38:41], v[180:183], v[220:223], v[38:41]
	v_mfma_f32_16x16x32_bf16 v[34:37], v[204:207], v[220:223], v[34:37]
	v_mfma_f32_16x16x32_bf16 v[22:25], v[180:183], v[228:231], v[22:25]
	v_mfma_f32_16x16x32_bf16 v[18:21], v[204:207], v[228:231], v[18:21]
	v_mfma_f32_16x16x32_bf16 v[6:9], v[180:183], v[236:239], v[6:9]
	v_mfma_f32_16x16x32_bf16 v[2:5], v[204:207], v[236:239], v[2:5]
	s_barrier
	s_setprio 0
	s_add_i32 s39, s39, 2
	s_add_u32 s10, s10, 0x100
	s_addc_u32 s11, s11, 0
	s_cmpk_gt_u32 s39, 0x55
	s_cbranch_scc0 .LBB0_1066
	s_add_u32 s10, s37, 0xffffff00
	s_addc_u32 s11, s38, -1
	s_and_b64 vcc, exec, s[2:3]
	s_cbranch_vccnz .LBB0_1053
	v_mov_b32_e32 v2, 0
	s_mov_b32 s21, s34
	s_mov_b32 s20, s35
	s_mov_b64 s[6:7], s[8:9]
	s_mov_b32 s33, s36
	v_mov_b32_e32 v3, v2
	v_mov_b32_e32 v4, v2
	v_mov_b32_e32 v5, v2
	v_mov_b32_e32 v6, v2
	v_mov_b32_e32 v7, v2
	v_mov_b32_e32 v8, v2
	v_mov_b32_e32 v9, v2
	v_mov_b32_e32 v18, v2
	v_mov_b32_e32 v19, v2
	v_mov_b32_e32 v20, v2
	v_mov_b32_e32 v21, v2
	v_mov_b32_e32 v22, v2
	v_mov_b32_e32 v23, v2
	v_mov_b32_e32 v24, v2
	v_mov_b32_e32 v25, v2
	v_mov_b32_e32 v34, v2
	v_mov_b32_e32 v35, v2
	v_mov_b32_e32 v36, v2
	v_mov_b32_e32 v37, v2
	v_mov_b32_e32 v38, v2
	v_mov_b32_e32 v39, v2
	v_mov_b32_e32 v40, v2
	v_mov_b32_e32 v41, v2
	v_mov_b32_e32 v50, v2
	v_mov_b32_e32 v51, v2
	v_mov_b32_e32 v52, v2
	v_mov_b32_e32 v53, v2
	v_mov_b32_e32 v54, v2
	v_mov_b32_e32 v55, v2
	v_mov_b32_e32 v56, v2
	v_mov_b32_e32 v57, v2
	v_mov_b32_e32 v10, v2
	v_mov_b32_e32 v11, v2
	v_mov_b32_e32 v12, v2
	v_mov_b32_e32 v13, v2
	v_mov_b32_e32 v14, v2
	v_mov_b32_e32 v15, v2
	v_mov_b32_e32 v16, v2
	v_mov_b32_e32 v17, v2
	v_mov_b32_e32 v26, v2
	v_mov_b32_e32 v27, v2
	v_mov_b32_e32 v28, v2
	v_mov_b32_e32 v29, v2
	v_mov_b32_e32 v30, v2
	v_mov_b32_e32 v31, v2
	v_mov_b32_e32 v32, v2
	v_mov_b32_e32 v33, v2
	v_mov_b32_e32 v42, v2
	v_mov_b32_e32 v43, v2
	v_mov_b32_e32 v44, v2
	v_mov_b32_e32 v45, v2
	v_mov_b32_e32 v46, v2
	v_mov_b32_e32 v47, v2
	v_mov_b32_e32 v48, v2
	v_mov_b32_e32 v49, v2
	v_mov_b32_e32 v58, v2
	v_mov_b32_e32 v59, v2
	v_mov_b32_e32 v60, v2
	v_mov_b32_e32 v61, v2
	v_mov_b32_e32 v62, v2
	v_mov_b32_e32 v63, v2
	v_mov_b32_e32 v64, v2
	v_mov_b32_e32 v65, v2
	v_mov_b32_e32 v66, v2
	v_mov_b32_e32 v67, v2
	v_mov_b32_e32 v68, v2
	v_mov_b32_e32 v69, v2
	v_mov_b32_e32 v70, v2
	v_mov_b32_e32 v71, v2
	v_mov_b32_e32 v72, v2
	v_mov_b32_e32 v73, v2
	v_mov_b32_e32 v82, v2
	v_mov_b32_e32 v83, v2
	v_mov_b32_e32 v84, v2
	v_mov_b32_e32 v85, v2
	v_mov_b32_e32 v86, v2
	v_mov_b32_e32 v87, v2
	v_mov_b32_e32 v88, v2
	v_mov_b32_e32 v89, v2
	v_mov_b32_e32 v98, v2
	v_mov_b32_e32 v99, v2
	v_mov_b32_e32 v100, v2
	v_mov_b32_e32 v101, v2
	v_mov_b32_e32 v102, v2
	v_mov_b32_e32 v103, v2
	v_mov_b32_e32 v104, v2
	v_mov_b32_e32 v105, v2
	v_mov_b32_e32 v114, v2
	v_mov_b32_e32 v115, v2
	v_mov_b32_e32 v116, v2
	v_mov_b32_e32 v117, v2
	v_mov_b32_e32 v118, v2
	v_mov_b32_e32 v119, v2
	v_mov_b32_e32 v120, v2
	v_mov_b32_e32 v121, v2
	v_mov_b32_e32 v74, v2
	v_mov_b32_e32 v75, v2
	v_mov_b32_e32 v76, v2
	v_mov_b32_e32 v77, v2
	v_mov_b32_e32 v78, v2
	v_mov_b32_e32 v79, v2
	v_mov_b32_e32 v80, v2
	v_mov_b32_e32 v81, v2
	v_mov_b32_e32 v90, v2
	v_mov_b32_e32 v91, v2
	v_mov_b32_e32 v92, v2
	v_mov_b32_e32 v93, v2
	v_mov_b32_e32 v94, v2
	v_mov_b32_e32 v95, v2
	v_mov_b32_e32 v96, v2
	v_mov_b32_e32 v97, v2
	v_mov_b32_e32 v106, v2
	v_mov_b32_e32 v107, v2
	v_mov_b32_e32 v108, v2
	v_mov_b32_e32 v109, v2
	v_mov_b32_e32 v110, v2
	v_mov_b32_e32 v111, v2
	v_mov_b32_e32 v112, v2
	v_mov_b32_e32 v113, v2
	v_mov_b32_e32 v122, v2
	v_mov_b32_e32 v123, v2
	v_mov_b32_e32 v124, v2
	v_mov_b32_e32 v125, v2
	v_mov_b32_e32 v126, v2
	v_mov_b32_e32 v127, v2
	v_mov_b32_e32 v128, v2
	v_mov_b32_e32 v129, v2
	s_andn2_b64 vcc, exec, s[0:1]
	s_cbranch_vccnz .LBB0_1054
